# vY + K-loop back-edge rotation (7.11): loop-control SALU and back-branch moved in front of the loop-back barrier in the 4 GEMM K-loops
# baseline (speedup 1.0000x reference)
.LBB0_107:
	s_ashr_i32 s95, s94, 31
	s_lshl_b64 s[6:7], s[94:95], 19
	s_add_u32 s90, s88, s6
	s_addc_u32 s91, s89, s7
	s_and_b64 s[6:7], s[38:39], exec
	s_cselect_b32 s6, s91, s5
	s_cselect_b32 s7, s90, s4
	s_ashr_i32 s37, s36, 31
	s_lshl_b64 s[40:41], s[36:37], 19
	s_add_u32 s96, s86, s40
	s_addc_u32 s97, s87, s41
	s_and_b64 s[40:41], s[38:39], exec
	s_cselect_b32 s37, s97, s1
	s_cselect_b32 s42, s96, s0
	s_add_u32 s40, s4, 0x40080
	s_addc_u32 s41, s5, 0
	s_add_u32 s43, s0, 0x100
	s_addc_u32 s46, s1, 0
	s_mov_b32 s47, -2
	s_cmp_eq_u32 s66, 1
	s_cbranch_scc0 .Lpeel_108
	v_mov_b32_e32 v0, 0
	v_mov_b32_e32 v1, v0
	v_mov_b32_e32 v2, v0
	v_mov_b32_e32 v3, v0
	v_mov_b32_e32 v4, v0
	v_mov_b32_e32 v5, v0
	v_mov_b32_e32 v6, v0
	v_mov_b32_e32 v7, v0
	v_mov_b32_e32 v16, v0
	v_mov_b32_e32 v17, v0
	v_mov_b32_e32 v18, v0
	v_mov_b32_e32 v19, v0
	v_mov_b32_e32 v20, v0
	v_mov_b32_e32 v21, v0
	v_mov_b32_e32 v22, v0
	v_mov_b32_e32 v23, v0
	v_mov_b32_e32 v32, v0
	v_mov_b32_e32 v33, v0
	v_mov_b32_e32 v34, v0
	v_mov_b32_e32 v35, v0
	v_mov_b32_e32 v36, v0
	v_mov_b32_e32 v37, v0
	v_mov_b32_e32 v38, v0
	v_mov_b32_e32 v39, v0
	v_mov_b32_e32 v64, v0
	v_mov_b32_e32 v65, v0
	v_mov_b32_e32 v66, v0
	v_mov_b32_e32 v67, v0
	v_mov_b32_e32 v68, v0
	v_mov_b32_e32 v69, v0
	v_mov_b32_e32 v70, v0
	v_mov_b32_e32 v71, v0
	v_mov_b32_e32 v8, v0
	v_mov_b32_e32 v9, v0
	v_mov_b32_e32 v10, v0
	v_mov_b32_e32 v11, v0
	v_mov_b32_e32 v12, v0
	v_mov_b32_e32 v13, v0
	v_mov_b32_e32 v14, v0
	v_mov_b32_e32 v15, v0
	v_mov_b32_e32 v24, v0
	v_mov_b32_e32 v25, v0
	v_mov_b32_e32 v26, v0
	v_mov_b32_e32 v27, v0
	v_mov_b32_e32 v28, v0
	v_mov_b32_e32 v29, v0
	v_mov_b32_e32 v30, v0
	v_mov_b32_e32 v31, v0
	v_mov_b32_e32 v48, v0
	v_mov_b32_e32 v49, v0
	v_mov_b32_e32 v50, v0
	v_mov_b32_e32 v51, v0
	v_mov_b32_e32 v52, v0
	v_mov_b32_e32 v53, v0
	v_mov_b32_e32 v54, v0
	v_mov_b32_e32 v55, v0
	v_mov_b32_e32 v72, v0
	v_mov_b32_e32 v73, v0
	v_mov_b32_e32 v74, v0
	v_mov_b32_e32 v75, v0
	v_mov_b32_e32 v76, v0
	v_mov_b32_e32 v77, v0
	v_mov_b32_e32 v78, v0
	v_mov_b32_e32 v79, v0
	v_mov_b32_e32 v80, v0
	v_mov_b32_e32 v81, v0
	v_mov_b32_e32 v82, v0
	v_mov_b32_e32 v83, v0
	v_mov_b32_e32 v84, v0
	v_mov_b32_e32 v85, v0
	v_mov_b32_e32 v86, v0
	v_mov_b32_e32 v87, v0
	v_mov_b32_e32 v128, v0
	v_mov_b32_e32 v129, v0
	v_mov_b32_e32 v130, v0
	v_mov_b32_e32 v131, v0
	v_mov_b32_e32 v132, v0
	v_mov_b32_e32 v133, v0
	v_mov_b32_e32 v134, v0
	v_mov_b32_e32 v135, v0
	v_mov_b32_e32 v96, v0
	v_mov_b32_e32 v97, v0
	v_mov_b32_e32 v98, v0
	v_mov_b32_e32 v99, v0
	v_mov_b32_e32 v100, v0
	v_mov_b32_e32 v101, v0
	v_mov_b32_e32 v102, v0
	v_mov_b32_e32 v103, v0
	v_mov_b32_e32 v144, v0
	v_mov_b32_e32 v145, v0
	v_mov_b32_e32 v146, v0
	v_mov_b32_e32 v147, v0
	v_mov_b32_e32 v148, v0
	v_mov_b32_e32 v149, v0
	v_mov_b32_e32 v150, v0
	v_mov_b32_e32 v151, v0
	v_mov_b32_e32 v88, v0
	v_mov_b32_e32 v89, v0
	v_mov_b32_e32 v90, v0
	v_mov_b32_e32 v91, v0
	v_mov_b32_e32 v92, v0
	v_mov_b32_e32 v93, v0
	v_mov_b32_e32 v94, v0
	v_mov_b32_e32 v95, v0
	v_mov_b32_e32 v136, v0
	v_mov_b32_e32 v137, v0
	v_mov_b32_e32 v138, v0
	v_mov_b32_e32 v139, v0
	v_mov_b32_e32 v140, v0
	v_mov_b32_e32 v141, v0
	v_mov_b32_e32 v142, v0
	v_mov_b32_e32 v143, v0
	v_mov_b32_e32 v108, v0
	v_mov_b32_e32 v109, v0
	v_mov_b32_e32 v110, v0
	v_mov_b32_e32 v111, v0
	v_mov_b32_e32 v116, v0
	v_mov_b32_e32 v117, v0
	v_mov_b32_e32 v118, v0
	v_mov_b32_e32 v119, v0
	v_mov_b32_e32 v160, v0
	v_mov_b32_e32 v161, v0
	v_mov_b32_e32 v162, v0
	v_mov_b32_e32 v163, v0
	v_mov_b32_e32 v164, v0
	v_mov_b32_e32 v165, v0
	v_mov_b32_e32 v166, v0
	v_mov_b32_e32 v167, v0
	s_waitcnt vmcnt(0)
	s_add_u32 s0, s40, 0xfffc0080
	s_addc_u32 s1, s41, -1
	s_add_i32 s68, 0, 0x10000
	s_cmp_eq_u32 s47, 12
	s_cselect_b32 s5, s6, s1
	s_cselect_b32 s4, s7, s0
	s_cselect_b32 s1, s37, s46
	s_cselect_b32 s0, s42, s43
	s_add_i32 s70, 0, 0x14000
	s_branch .Lrot_body_108
.Lpeel_108:
	s_add_u32 s0, s40, 0xfffc0080
	s_addc_u32 s1, s41, -1
	s_add_i32 s68, 0, 0x10000
	s_cmp_eq_u32 s47, 12
	s_cselect_b32 s5, s6, s1
	s_cselect_b32 s4, s7, s0
	s_cselect_b32 s1, s37, s46
	s_cselect_b32 s0, s42, s43
	s_add_i32 s70, 0, 0x14000
	v_add_u32_e32 v60, s68, v250
	v_add_u32_e32 v124, s70, v250
	ds_read_b128 v[40:43], v60
	ds_read_b128 v[44:47], v60 offset:1024
	ds_read_b128 v[56:59], v60 offset:2048
	ds_read_b128 v[60:63], v60 offset:3072
	ds_read_b128 v[104:107], v124
	ds_read_b128 v[112:115], v124 offset:1024
	ds_read_b128 v[120:123], v124 offset:2048
	ds_read_b128 v[124:127], v124 offset:3072
	s_add_i32 m0, s20, 0xc000
	ds_read_b128 v[152:155], v251
	ds_read_b128 v[156:159], v251 offset:1024
	ds_read_b128 v[168:171], v251 offset:2048
	ds_read_b128 v[172:175], v251 offset:3072
	ds_read_b128 v[200:203], v251 offset:4096
	ds_read_b128 v[204:207], v251 offset:5120
	ds_read_b128 v[208:211], v251 offset:6144
	ds_read_b128 v[212:215], v251 offset:7168
	global_load_lds_dwordx4 v196, s[40:41]
	s_add_i32 m0, s20, 0xe000
	s_nop 0
	global_load_lds_dwordx4 v198, s[40:41]
	s_waitcnt vmcnt(8)
	s_waitcnt lgkmcnt(0)
	s_barrier
	s_waitcnt lgkmcnt(0)
	v_mfma_f32_16x16x32_bf16 v[164:167], v[40:43], v[152:155], 0
	v_mfma_f32_16x16x32_bf16 v[160:163], v[56:59], v[152:155], 0
	v_mfma_f32_16x16x32_bf16 v[116:119], v[40:43], v[168:171], 0
	v_mfma_f32_16x16x32_bf16 v[108:111], v[56:59], v[168:171], 0
	v_mfma_f32_16x16x32_bf16 v[140:143], v[40:43], v[200:203], 0
	v_mfma_f32_16x16x32_bf16 v[136:139], v[56:59], v[200:203], 0
	v_mfma_f32_16x16x32_bf16 v[92:95], v[40:43], v[208:211], 0
	v_mfma_f32_16x16x32_bf16 v[88:91], v[56:59], v[208:211], 0
	v_mfma_f32_16x16x32_bf16 v[164:167], v[44:47], v[156:159], v[164:167]
	v_mfma_f32_16x16x32_bf16 v[160:163], v[60:63], v[156:159], v[160:163]
	v_mfma_f32_16x16x32_bf16 v[116:119], v[44:47], v[172:175], v[116:119]
	v_mfma_f32_16x16x32_bf16 v[108:111], v[60:63], v[172:175], v[108:111]
	v_mfma_f32_16x16x32_bf16 v[140:143], v[44:47], v[204:207], v[140:143]
	v_mfma_f32_16x16x32_bf16 v[136:139], v[60:63], v[204:207], v[136:139]
	v_mfma_f32_16x16x32_bf16 v[92:95], v[44:47], v[212:215], v[92:95]
	v_mfma_f32_16x16x32_bf16 v[88:91], v[60:63], v[212:215], v[88:91]
	v_mfma_f32_16x16x32_bf16 v[148:151], v[104:107], v[152:155], 0
	v_mfma_f32_16x16x32_bf16 v[144:147], v[120:123], v[152:155], 0
	v_mfma_f32_16x16x32_bf16 v[100:103], v[104:107], v[168:171], 0
	v_mfma_f32_16x16x32_bf16 v[96:99], v[120:123], v[168:171], 0
	v_mfma_f32_16x16x32_bf16 v[132:135], v[104:107], v[200:203], 0
	v_mfma_f32_16x16x32_bf16 v[128:131], v[120:123], v[200:203], 0
	v_mfma_f32_16x16x32_bf16 v[84:87], v[104:107], v[208:211], 0
	v_mfma_f32_16x16x32_bf16 v[80:83], v[120:123], v[208:211], 0
	v_mfma_f32_16x16x32_bf16 v[148:151], v[112:115], v[156:159], v[148:151]
	v_mfma_f32_16x16x32_bf16 v[144:147], v[124:127], v[156:159], v[144:147]
	v_mfma_f32_16x16x32_bf16 v[100:103], v[112:115], v[172:175], v[100:103]
	v_mfma_f32_16x16x32_bf16 v[96:99], v[124:127], v[172:175], v[96:99]
	v_mfma_f32_16x16x32_bf16 v[132:135], v[112:115], v[204:207], v[132:135]
	v_mfma_f32_16x16x32_bf16 v[128:131], v[124:127], v[204:207], v[128:131]
	v_mfma_f32_16x16x32_bf16 v[84:87], v[112:115], v[212:215], v[84:87]
	v_mfma_f32_16x16x32_bf16 v[80:83], v[124:127], v[212:215], v[80:83]
	s_barrier
	s_add_i32 s68, s68, s27
	v_lshl_add_u64 v[178:179], s[0:1], 0, v[176:177]
	s_mov_b32 m0, s68
	ds_read_b128 v[152:155], v251 offset:16384
	ds_read_b128 v[156:159], v251 offset:17408
	ds_read_b128 v[168:171], v251 offset:18432
	ds_read_b128 v[172:175], v251 offset:19456
	ds_read_b128 v[200:203], v251 offset:20480
	ds_read_b128 v[204:207], v251 offset:21504
	ds_read_b128 v[208:211], v251 offset:22528
	ds_read_b128 v[212:215], v251 offset:23552
	global_load_lds_dwordx4 v176, s[0:1]
	s_add_i32 m0, s68, 0x2000
	s_add_u32 s68, s0, 0x40000
	v_lshl_add_u64 v[180:181], s[0:1], 0, v[190:191]
	s_addc_u32 s69, s1, 0
	s_add_i32 s70, s70, s27
	global_load_lds_dwordx4 v190, s[0:1]
	s_mov_b32 m0, s70
	v_lshl_add_u64 v[188:189], s[4:5], 0, v[192:193]
	global_load_lds_dwordx4 v176, s[68:69]
	s_add_i32 m0, s70, 0x2000
	s_nop 0
	global_load_lds_dwordx4 v190, s[68:69]
	v_lshl_add_u64 v[186:187], s[4:5], 0, v[194:195]
	s_mov_b32 m0, s20
	s_nop 0
	global_load_lds_dwordx4 v194, s[4:5]
	s_mov_b32 m0, s12
	s_nop 0
	global_load_lds_dwordx4 v192, s[4:5]
	s_waitcnt vmcnt(8)
	s_waitcnt lgkmcnt(0)
	s_barrier
	s_waitcnt lgkmcnt(0)
	v_mfma_f32_16x16x32_bf16 v[76:79], v[40:43], v[152:155], 0
	v_mfma_f32_16x16x32_bf16 v[72:75], v[56:59], v[152:155], 0
	v_mfma_f32_16x16x32_bf16 v[52:55], v[40:43], v[168:171], 0
	v_mfma_f32_16x16x32_bf16 v[48:51], v[56:59], v[168:171], 0
	v_mfma_f32_16x16x32_bf16 v[28:31], v[40:43], v[200:203], 0
	v_mfma_f32_16x16x32_bf16 v[24:27], v[56:59], v[200:203], 0
	v_mfma_f32_16x16x32_bf16 v[12:15], v[40:43], v[208:211], 0
	v_mfma_f32_16x16x32_bf16 v[8:11], v[56:59], v[208:211], 0
	v_mfma_f32_16x16x32_bf16 v[76:79], v[44:47], v[156:159], v[76:79]
	v_mfma_f32_16x16x32_bf16 v[72:75], v[60:63], v[156:159], v[72:75]
	v_mfma_f32_16x16x32_bf16 v[52:55], v[44:47], v[172:175], v[52:55]
	v_mfma_f32_16x16x32_bf16 v[48:51], v[60:63], v[172:175], v[48:51]
	v_mfma_f32_16x16x32_bf16 v[28:31], v[44:47], v[204:207], v[28:31]
	v_mfma_f32_16x16x32_bf16 v[24:27], v[60:63], v[204:207], v[24:27]
	v_mfma_f32_16x16x32_bf16 v[12:15], v[44:47], v[212:215], v[12:15]
	v_mfma_f32_16x16x32_bf16 v[8:11], v[60:63], v[212:215], v[8:11]
	v_mfma_f32_16x16x32_bf16 v[36:39], v[104:107], v[168:171], 0
	v_mfma_f32_16x16x32_bf16 v[32:35], v[120:123], v[168:171], 0
	v_mfma_f32_16x16x32_bf16 v[20:23], v[104:107], v[200:203], 0
	v_mfma_f32_16x16x32_bf16 v[16:19], v[120:123], v[200:203], 0
	v_mfma_f32_16x16x32_bf16 v[4:7], v[104:107], v[208:211], 0
	v_mfma_f32_16x16x32_bf16 v[0:3], v[120:123], v[208:211], 0
	v_mfma_f32_16x16x32_bf16 v[40:43], v[104:107], v[152:155], 0
	v_mfma_f32_16x16x32_bf16 v[44:47], v[120:123], v[152:155], 0
	v_mfma_f32_16x16x32_bf16 v[36:39], v[112:115], v[172:175], v[36:39]
	v_mfma_f32_16x16x32_bf16 v[32:35], v[124:127], v[172:175], v[32:35]
	v_mfma_f32_16x16x32_bf16 v[20:23], v[112:115], v[204:207], v[20:23]
	v_mfma_f32_16x16x32_bf16 v[16:19], v[124:127], v[204:207], v[16:19]
	v_mfma_f32_16x16x32_bf16 v[4:7], v[112:115], v[212:215], v[4:7]
	v_mfma_f32_16x16x32_bf16 v[0:3], v[124:127], v[212:215], v[0:3]
	v_mfma_f32_16x16x32_bf16 v[40:43], v[112:115], v[156:159], v[40:43]
	v_mfma_f32_16x16x32_bf16 v[44:47], v[124:127], v[156:159], v[44:47]
	s_barrier
	s_add_i32 s68, 0, 0x18000
	s_add_i32 s69, 0, 0x1c000
	v_add_u32_e32 v68, s68, v250
	v_add_u32_e32 v124, s69, v250
	ds_read_b128 v[56:59], v68
	ds_read_b128 v[60:63], v68 offset:1024
	ds_read_b128 v[64:67], v68 offset:2048
	ds_read_b128 v[68:71], v68 offset:3072
	ds_read_b128 v[104:107], v124
	ds_read_b128 v[112:115], v124 offset:1024
	ds_read_b128 v[120:123], v124 offset:2048
	ds_read_b128 v[124:127], v124 offset:3072
	s_add_u32 s4, s4, 0x40000
	s_addc_u32 s5, s5, 0
	s_mov_b32 m0, s60
	ds_read_b128 v[152:155], v251 offset:32768
	ds_read_b128 v[156:159], v251 offset:33792
	ds_read_b128 v[168:171], v251 offset:34816
	ds_read_b128 v[172:175], v251 offset:35840
	ds_read_b128 v[200:203], v251 offset:36864
	ds_read_b128 v[204:207], v251 offset:37888
	ds_read_b128 v[208:211], v251 offset:38912
	ds_read_b128 v[212:215], v251 offset:39936
	global_load_lds_dwordx4 v194, s[4:5]
	s_mov_b32 m0, s61
	s_nop 0
	global_load_lds_dwordx4 v192, s[4:5]
	s_waitcnt vmcnt(8)
	s_waitcnt lgkmcnt(0)
	s_barrier
	s_waitcnt lgkmcnt(0)
	v_mfma_f32_16x16x32_bf16 v[164:167], v[56:59], v[152:155], v[164:167]
	v_mfma_f32_16x16x32_bf16 v[160:163], v[64:67], v[152:155], v[160:163]
	v_mfma_f32_16x16x32_bf16 v[116:119], v[56:59], v[168:171], v[116:119]
	v_mfma_f32_16x16x32_bf16 v[108:111], v[64:67], v[168:171], v[108:111]
	v_mfma_f32_16x16x32_bf16 v[140:143], v[56:59], v[200:203], v[140:143]
	v_mfma_f32_16x16x32_bf16 v[136:139], v[64:67], v[200:203], v[136:139]
	v_mfma_f32_16x16x32_bf16 v[92:95], v[56:59], v[208:211], v[92:95]
	v_mfma_f32_16x16x32_bf16 v[88:91], v[64:67], v[208:211], v[88:91]
	v_mfma_f32_16x16x32_bf16 v[164:167], v[60:63], v[156:159], v[164:167]
	v_mfma_f32_16x16x32_bf16 v[160:163], v[68:71], v[156:159], v[160:163]
	v_mfma_f32_16x16x32_bf16 v[116:119], v[60:63], v[172:175], v[116:119]
	v_mfma_f32_16x16x32_bf16 v[108:111], v[68:71], v[172:175], v[108:111]
	v_mfma_f32_16x16x32_bf16 v[140:143], v[60:63], v[204:207], v[140:143]
	v_mfma_f32_16x16x32_bf16 v[136:139], v[68:71], v[204:207], v[136:139]
	v_mfma_f32_16x16x32_bf16 v[92:95], v[60:63], v[212:215], v[92:95]
	v_mfma_f32_16x16x32_bf16 v[88:91], v[68:71], v[212:215], v[88:91]
	v_mfma_f32_16x16x32_bf16 v[148:151], v[104:107], v[152:155], v[148:151]
	v_mfma_f32_16x16x32_bf16 v[144:147], v[120:123], v[152:155], v[144:147]
	v_mfma_f32_16x16x32_bf16 v[100:103], v[104:107], v[168:171], v[100:103]
	v_mfma_f32_16x16x32_bf16 v[96:99], v[120:123], v[168:171], v[96:99]
	v_mfma_f32_16x16x32_bf16 v[132:135], v[104:107], v[200:203], v[132:135]
	v_mfma_f32_16x16x32_bf16 v[128:131], v[120:123], v[200:203], v[128:131]
	v_mfma_f32_16x16x32_bf16 v[84:87], v[104:107], v[208:211], v[84:87]
	v_mfma_f32_16x16x32_bf16 v[80:83], v[120:123], v[208:211], v[80:83]
	v_mfma_f32_16x16x32_bf16 v[148:151], v[112:115], v[156:159], v[148:151]
	v_mfma_f32_16x16x32_bf16 v[144:147], v[124:127], v[156:159], v[144:147]
	v_mfma_f32_16x16x32_bf16 v[100:103], v[112:115], v[172:175], v[100:103]
	v_mfma_f32_16x16x32_bf16 v[96:99], v[124:127], v[172:175], v[96:99]
	v_mfma_f32_16x16x32_bf16 v[132:135], v[112:115], v[204:207], v[132:135]
	v_mfma_f32_16x16x32_bf16 v[128:131], v[124:127], v[204:207], v[128:131]
	v_mfma_f32_16x16x32_bf16 v[84:87], v[112:115], v[212:215], v[84:87]
	v_mfma_f32_16x16x32_bf16 v[80:83], v[124:127], v[212:215], v[80:83]
	s_barrier
	s_add_i32 s4, s68, s27
	v_lshl_add_u64 v[178:179], v[178:179], 0, s[82:83]
	s_mov_b32 m0, s4
	ds_read_b128 v[152:155], v251 offset:49152
	ds_read_b128 v[156:159], v251 offset:50176
	ds_read_b128 v[168:171], v251 offset:51200
	ds_read_b128 v[172:175], v251 offset:52224
	ds_read_b128 v[200:203], v251 offset:53248
	ds_read_b128 v[204:207], v251 offset:54272
	ds_read_b128 v[208:211], v251 offset:55296
	ds_read_b128 v[212:215], v251 offset:56320
	global_load_lds_dwordx4 v[178:179], off
	s_add_i32 m0, s4, 0x2000
	s_add_u32 s0, s0, 0x40080
	v_lshl_add_u64 v[178:179], v[180:181], 0, s[82:83]
	s_addc_u32 s1, s1, 0
	s_add_i32 s4, s69, s27
	global_load_lds_dwordx4 v[178:179], off
	s_mov_b32 m0, s4
	s_nop 0
	global_load_lds_dwordx4 v176, s[0:1]
	s_add_i32 m0, s4, 0x2000
	s_nop 0
	global_load_lds_dwordx4 v190, s[0:1]
	v_lshl_add_u64 v[178:179], v[186:187], 0, s[82:83]
	s_mov_b32 m0, s64
	s_nop 0
	global_load_lds_dwordx4 v[178:179], off
	v_lshl_add_u64 v[178:179], v[188:189], 0, s[82:83]
	s_mov_b32 m0, s65
	s_nop 0
	global_load_lds_dwordx4 v[178:179], off
	s_waitcnt vmcnt(8)
	s_waitcnt lgkmcnt(0)
	s_barrier
	s_waitcnt lgkmcnt(0)
	v_mfma_f32_16x16x32_bf16 v[76:79], v[56:59], v[152:155], v[76:79]
	v_mfma_f32_16x16x32_bf16 v[72:75], v[64:67], v[152:155], v[72:75]
	v_mfma_f32_16x16x32_bf16 v[52:55], v[56:59], v[168:171], v[52:55]
	v_mfma_f32_16x16x32_bf16 v[48:51], v[64:67], v[168:171], v[48:51]
	v_mfma_f32_16x16x32_bf16 v[28:31], v[56:59], v[200:203], v[28:31]
	v_mfma_f32_16x16x32_bf16 v[24:27], v[64:67], v[200:203], v[24:27]
	v_mfma_f32_16x16x32_bf16 v[12:15], v[56:59], v[208:211], v[12:15]
	v_mfma_f32_16x16x32_bf16 v[8:11], v[64:67], v[208:211], v[8:11]
	v_mfma_f32_16x16x32_bf16 v[76:79], v[60:63], v[156:159], v[76:79]
	v_mfma_f32_16x16x32_bf16 v[72:75], v[68:71], v[156:159], v[72:75]
	v_mfma_f32_16x16x32_bf16 v[52:55], v[60:63], v[172:175], v[52:55]
	v_mfma_f32_16x16x32_bf16 v[48:51], v[68:71], v[172:175], v[48:51]
	v_mfma_f32_16x16x32_bf16 v[28:31], v[60:63], v[204:207], v[28:31]
	v_mfma_f32_16x16x32_bf16 v[24:27], v[68:71], v[204:207], v[24:27]
	v_mfma_f32_16x16x32_bf16 v[12:15], v[60:63], v[212:215], v[12:15]
	v_mfma_f32_16x16x32_bf16 v[8:11], v[68:71], v[212:215], v[8:11]
	v_mfma_f32_16x16x32_bf16 v[40:43], v[104:107], v[152:155], v[40:43]
	v_mfma_f32_16x16x32_bf16 v[68:71], v[112:115], v[156:159], v[40:43]
	v_mfma_f32_16x16x32_bf16 v[40:43], v[120:123], v[152:155], v[44:47]
	v_mfma_f32_16x16x32_bf16 v[36:39], v[104:107], v[168:171], v[36:39]
	v_mfma_f32_16x16x32_bf16 v[32:35], v[120:123], v[168:171], v[32:35]
	v_mfma_f32_16x16x32_bf16 v[20:23], v[104:107], v[200:203], v[20:23]
	v_mfma_f32_16x16x32_bf16 v[16:19], v[120:123], v[200:203], v[16:19]
	v_mfma_f32_16x16x32_bf16 v[4:7], v[104:107], v[208:211], v[4:7]
	v_mfma_f32_16x16x32_bf16 v[0:3], v[120:123], v[208:211], v[0:3]
	v_mfma_f32_16x16x32_bf16 v[64:67], v[124:127], v[156:159], v[40:43]
	v_mfma_f32_16x16x32_bf16 v[36:39], v[112:115], v[172:175], v[36:39]
	v_mfma_f32_16x16x32_bf16 v[32:35], v[124:127], v[172:175], v[32:35]
	v_mfma_f32_16x16x32_bf16 v[20:23], v[112:115], v[204:207], v[20:23]
	v_mfma_f32_16x16x32_bf16 v[16:19], v[124:127], v[204:207], v[16:19]
	v_mfma_f32_16x16x32_bf16 v[4:7], v[112:115], v[212:215], v[4:7]
	v_mfma_f32_16x16x32_bf16 v[0:3], v[124:127], v[212:215], v[0:3]
	s_add_i32 s47, s47, 2
	s_add_u32 s40, s40, 0x100
	s_addc_u32 s41, s41, 0
	s_add_u32 s43, s43, 0x100
	s_addc_u32 s46, s46, 0
.LBB0_108:
	s_add_u32 s0, s40, 0xfffc0080
	s_addc_u32 s1, s41, -1
	s_add_i32 s68, 0, 0x10000
	s_cmp_eq_u32 s47, 12
	s_cselect_b32 s5, s6, s1
	s_cselect_b32 s4, s7, s0
	s_cselect_b32 s1, s37, s46
	s_cselect_b32 s0, s42, s43
	s_add_i32 s70, 0, 0x14000
	s_barrier
.Lrot_body_108:
	v_add_u32_e32 v60, s68, v250
	v_add_u32_e32 v124, s70, v250
	ds_read_b128 v[40:43], v60
	ds_read_b128 v[44:47], v60 offset:1024
	ds_read_b128 v[56:59], v60 offset:2048
	ds_read_b128 v[60:63], v60 offset:3072
	ds_read_b128 v[104:107], v124
	ds_read_b128 v[112:115], v124 offset:1024
	ds_read_b128 v[120:123], v124 offset:2048
	ds_read_b128 v[124:127], v124 offset:3072
	s_add_i32 m0, s20, 0xc000
	ds_read_b128 v[152:155], v251
	ds_read_b128 v[156:159], v251 offset:1024
	ds_read_b128 v[168:171], v251 offset:2048
	ds_read_b128 v[172:175], v251 offset:3072
	ds_read_b128 v[200:203], v251 offset:4096
	ds_read_b128 v[204:207], v251 offset:5120
	ds_read_b128 v[208:211], v251 offset:6144
	ds_read_b128 v[212:215], v251 offset:7168
	global_load_lds_dwordx4 v196, s[40:41]
	s_add_i32 m0, s20, 0xe000
	s_nop 0
	global_load_lds_dwordx4 v198, s[40:41]
	s_waitcnt vmcnt(8)
	s_waitcnt lgkmcnt(0)
	s_barrier
	s_waitcnt lgkmcnt(0)
	v_mfma_f32_16x16x32_bf16 v[164:167], v[40:43], v[152:155], v[164:167]
	v_mfma_f32_16x16x32_bf16 v[160:163], v[56:59], v[152:155], v[160:163]
	v_mfma_f32_16x16x32_bf16 v[116:119], v[40:43], v[168:171], v[116:119]
	v_mfma_f32_16x16x32_bf16 v[108:111], v[56:59], v[168:171], v[108:111]
	v_mfma_f32_16x16x32_bf16 v[140:143], v[40:43], v[200:203], v[140:143]
	v_mfma_f32_16x16x32_bf16 v[136:139], v[56:59], v[200:203], v[136:139]
	v_mfma_f32_16x16x32_bf16 v[92:95], v[40:43], v[208:211], v[92:95]
	v_mfma_f32_16x16x32_bf16 v[88:91], v[56:59], v[208:211], v[88:91]
	v_mfma_f32_16x16x32_bf16 v[164:167], v[44:47], v[156:159], v[164:167]
	v_mfma_f32_16x16x32_bf16 v[160:163], v[60:63], v[156:159], v[160:163]
	v_mfma_f32_16x16x32_bf16 v[116:119], v[44:47], v[172:175], v[116:119]
	v_mfma_f32_16x16x32_bf16 v[108:111], v[60:63], v[172:175], v[108:111]
	v_mfma_f32_16x16x32_bf16 v[140:143], v[44:47], v[204:207], v[140:143]
	v_mfma_f32_16x16x32_bf16 v[136:139], v[60:63], v[204:207], v[136:139]
	v_mfma_f32_16x16x32_bf16 v[92:95], v[44:47], v[212:215], v[92:95]
	v_mfma_f32_16x16x32_bf16 v[88:91], v[60:63], v[212:215], v[88:91]
	v_mfma_f32_16x16x32_bf16 v[148:151], v[104:107], v[152:155], v[148:151]
	v_mfma_f32_16x16x32_bf16 v[144:147], v[120:123], v[152:155], v[144:147]
	v_mfma_f32_16x16x32_bf16 v[100:103], v[104:107], v[168:171], v[100:103]
	v_mfma_f32_16x16x32_bf16 v[96:99], v[120:123], v[168:171], v[96:99]
	v_mfma_f32_16x16x32_bf16 v[132:135], v[104:107], v[200:203], v[132:135]
	v_mfma_f32_16x16x32_bf16 v[128:131], v[120:123], v[200:203], v[128:131]
	v_mfma_f32_16x16x32_bf16 v[84:87], v[104:107], v[208:211], v[84:87]
	v_mfma_f32_16x16x32_bf16 v[80:83], v[120:123], v[208:211], v[80:83]
	v_mfma_f32_16x16x32_bf16 v[148:151], v[112:115], v[156:159], v[148:151]
	v_mfma_f32_16x16x32_bf16 v[144:147], v[124:127], v[156:159], v[144:147]
	v_mfma_f32_16x16x32_bf16 v[100:103], v[112:115], v[172:175], v[100:103]
	v_mfma_f32_16x16x32_bf16 v[96:99], v[124:127], v[172:175], v[96:99]
	v_mfma_f32_16x16x32_bf16 v[132:135], v[112:115], v[204:207], v[132:135]
	v_mfma_f32_16x16x32_bf16 v[128:131], v[124:127], v[204:207], v[128:131]
	v_mfma_f32_16x16x32_bf16 v[84:87], v[112:115], v[212:215], v[84:87]
	v_mfma_f32_16x16x32_bf16 v[80:83], v[124:127], v[212:215], v[80:83]
	s_barrier
	s_add_i32 s68, s68, s27
	v_lshl_add_u64 v[178:179], s[0:1], 0, v[176:177]
	s_mov_b32 m0, s68
	ds_read_b128 v[152:155], v251 offset:16384
	ds_read_b128 v[156:159], v251 offset:17408
	ds_read_b128 v[168:171], v251 offset:18432
	ds_read_b128 v[172:175], v251 offset:19456
	ds_read_b128 v[200:203], v251 offset:20480
	ds_read_b128 v[204:207], v251 offset:21504
	ds_read_b128 v[208:211], v251 offset:22528
	ds_read_b128 v[212:215], v251 offset:23552
	global_load_lds_dwordx4 v176, s[0:1]
	s_add_i32 m0, s68, 0x2000
	s_add_u32 s68, s0, 0x40000
	v_lshl_add_u64 v[180:181], s[0:1], 0, v[190:191]
	s_addc_u32 s69, s1, 0
	s_add_i32 s70, s70, s27
	global_load_lds_dwordx4 v190, s[0:1]
	s_mov_b32 m0, s70
	v_lshl_add_u64 v[188:189], s[4:5], 0, v[192:193]
	global_load_lds_dwordx4 v176, s[68:69]
	s_add_i32 m0, s70, 0x2000
	s_nop 0
	global_load_lds_dwordx4 v190, s[68:69]
	v_lshl_add_u64 v[186:187], s[4:5], 0, v[194:195]
	s_mov_b32 m0, s20
	s_nop 0
	global_load_lds_dwordx4 v194, s[4:5]
	s_mov_b32 m0, s12
	s_nop 0
	global_load_lds_dwordx4 v192, s[4:5]
	s_waitcnt vmcnt(8)
	s_waitcnt lgkmcnt(0)
	s_barrier
	s_waitcnt lgkmcnt(0)
	v_mfma_f32_16x16x32_bf16 v[76:79], v[40:43], v[152:155], v[76:79]
	v_mfma_f32_16x16x32_bf16 v[72:75], v[56:59], v[152:155], v[72:75]
	v_mfma_f32_16x16x32_bf16 v[52:55], v[40:43], v[168:171], v[52:55]
	v_mfma_f32_16x16x32_bf16 v[48:51], v[56:59], v[168:171], v[48:51]
	v_mfma_f32_16x16x32_bf16 v[28:31], v[40:43], v[200:203], v[28:31]
	v_mfma_f32_16x16x32_bf16 v[24:27], v[56:59], v[200:203], v[24:27]
	v_mfma_f32_16x16x32_bf16 v[12:15], v[40:43], v[208:211], v[12:15]
	v_mfma_f32_16x16x32_bf16 v[8:11], v[56:59], v[208:211], v[8:11]
	v_mfma_f32_16x16x32_bf16 v[76:79], v[44:47], v[156:159], v[76:79]
	v_mfma_f32_16x16x32_bf16 v[72:75], v[60:63], v[156:159], v[72:75]
	v_mfma_f32_16x16x32_bf16 v[52:55], v[44:47], v[172:175], v[52:55]
	v_mfma_f32_16x16x32_bf16 v[48:51], v[60:63], v[172:175], v[48:51]
	v_mfma_f32_16x16x32_bf16 v[28:31], v[44:47], v[204:207], v[28:31]
	v_mfma_f32_16x16x32_bf16 v[24:27], v[60:63], v[204:207], v[24:27]
	v_mfma_f32_16x16x32_bf16 v[12:15], v[44:47], v[212:215], v[12:15]
	v_mfma_f32_16x16x32_bf16 v[8:11], v[60:63], v[212:215], v[8:11]
	v_mfma_f32_16x16x32_bf16 v[36:39], v[104:107], v[168:171], v[36:39]
	v_mfma_f32_16x16x32_bf16 v[32:35], v[120:123], v[168:171], v[32:35]
	v_mfma_f32_16x16x32_bf16 v[20:23], v[104:107], v[200:203], v[20:23]
	v_mfma_f32_16x16x32_bf16 v[16:19], v[120:123], v[200:203], v[16:19]
	v_mfma_f32_16x16x32_bf16 v[4:7], v[104:107], v[208:211], v[4:7]
	v_mfma_f32_16x16x32_bf16 v[0:3], v[120:123], v[208:211], v[0:3]
	v_mfma_f32_16x16x32_bf16 v[40:43], v[104:107], v[152:155], v[68:71]
	v_mfma_f32_16x16x32_bf16 v[44:47], v[120:123], v[152:155], v[64:67]
	v_mfma_f32_16x16x32_bf16 v[36:39], v[112:115], v[172:175], v[36:39]
	v_mfma_f32_16x16x32_bf16 v[32:35], v[124:127], v[172:175], v[32:35]
	v_mfma_f32_16x16x32_bf16 v[20:23], v[112:115], v[204:207], v[20:23]
	v_mfma_f32_16x16x32_bf16 v[16:19], v[124:127], v[204:207], v[16:19]
	v_mfma_f32_16x16x32_bf16 v[4:7], v[112:115], v[212:215], v[4:7]
	v_mfma_f32_16x16x32_bf16 v[0:3], v[124:127], v[212:215], v[0:3]
	v_mfma_f32_16x16x32_bf16 v[40:43], v[112:115], v[156:159], v[40:43]
	v_mfma_f32_16x16x32_bf16 v[44:47], v[124:127], v[156:159], v[44:47]
	s_barrier
	s_add_i32 s68, 0, 0x18000
	s_add_i32 s69, 0, 0x1c000
	v_add_u32_e32 v68, s68, v250
	v_add_u32_e32 v124, s69, v250
	ds_read_b128 v[56:59], v68
	ds_read_b128 v[60:63], v68 offset:1024
	ds_read_b128 v[64:67], v68 offset:2048
	ds_read_b128 v[68:71], v68 offset:3072
	ds_read_b128 v[104:107], v124
	ds_read_b128 v[112:115], v124 offset:1024
	ds_read_b128 v[120:123], v124 offset:2048
	ds_read_b128 v[124:127], v124 offset:3072
	s_add_u32 s4, s4, 0x40000
	s_addc_u32 s5, s5, 0
	s_mov_b32 m0, s60
	ds_read_b128 v[152:155], v251 offset:32768
	ds_read_b128 v[156:159], v251 offset:33792
	ds_read_b128 v[168:171], v251 offset:34816
	ds_read_b128 v[172:175], v251 offset:35840
	ds_read_b128 v[200:203], v251 offset:36864
	ds_read_b128 v[204:207], v251 offset:37888
	ds_read_b128 v[208:211], v251 offset:38912
	ds_read_b128 v[212:215], v251 offset:39936
	global_load_lds_dwordx4 v194, s[4:5]
	s_mov_b32 m0, s61
	s_nop 0
	global_load_lds_dwordx4 v192, s[4:5]
	s_waitcnt vmcnt(8)
	s_waitcnt lgkmcnt(0)
	s_barrier
	s_waitcnt lgkmcnt(0)
	v_mfma_f32_16x16x32_bf16 v[164:167], v[56:59], v[152:155], v[164:167]
	v_mfma_f32_16x16x32_bf16 v[160:163], v[64:67], v[152:155], v[160:163]
	v_mfma_f32_16x16x32_bf16 v[116:119], v[56:59], v[168:171], v[116:119]
	v_mfma_f32_16x16x32_bf16 v[108:111], v[64:67], v[168:171], v[108:111]
	v_mfma_f32_16x16x32_bf16 v[140:143], v[56:59], v[200:203], v[140:143]
	v_mfma_f32_16x16x32_bf16 v[136:139], v[64:67], v[200:203], v[136:139]
	v_mfma_f32_16x16x32_bf16 v[92:95], v[56:59], v[208:211], v[92:95]
	v_mfma_f32_16x16x32_bf16 v[88:91], v[64:67], v[208:211], v[88:91]
	v_mfma_f32_16x16x32_bf16 v[164:167], v[60:63], v[156:159], v[164:167]
	v_mfma_f32_16x16x32_bf16 v[160:163], v[68:71], v[156:159], v[160:163]
	v_mfma_f32_16x16x32_bf16 v[116:119], v[60:63], v[172:175], v[116:119]
	v_mfma_f32_16x16x32_bf16 v[108:111], v[68:71], v[172:175], v[108:111]
	v_mfma_f32_16x16x32_bf16 v[140:143], v[60:63], v[204:207], v[140:143]
	v_mfma_f32_16x16x32_bf16 v[136:139], v[68:71], v[204:207], v[136:139]
	v_mfma_f32_16x16x32_bf16 v[92:95], v[60:63], v[212:215], v[92:95]
	v_mfma_f32_16x16x32_bf16 v[88:91], v[68:71], v[212:215], v[88:91]
	v_mfma_f32_16x16x32_bf16 v[148:151], v[104:107], v[152:155], v[148:151]
	v_mfma_f32_16x16x32_bf16 v[144:147], v[120:123], v[152:155], v[144:147]
	v_mfma_f32_16x16x32_bf16 v[100:103], v[104:107], v[168:171], v[100:103]
	v_mfma_f32_16x16x32_bf16 v[96:99], v[120:123], v[168:171], v[96:99]
	v_mfma_f32_16x16x32_bf16 v[132:135], v[104:107], v[200:203], v[132:135]
	v_mfma_f32_16x16x32_bf16 v[128:131], v[120:123], v[200:203], v[128:131]
	v_mfma_f32_16x16x32_bf16 v[84:87], v[104:107], v[208:211], v[84:87]
	v_mfma_f32_16x16x32_bf16 v[80:83], v[120:123], v[208:211], v[80:83]
	v_mfma_f32_16x16x32_bf16 v[148:151], v[112:115], v[156:159], v[148:151]
	v_mfma_f32_16x16x32_bf16 v[144:147], v[124:127], v[156:159], v[144:147]
	v_mfma_f32_16x16x32_bf16 v[100:103], v[112:115], v[172:175], v[100:103]
	v_mfma_f32_16x16x32_bf16 v[96:99], v[124:127], v[172:175], v[96:99]
	v_mfma_f32_16x16x32_bf16 v[132:135], v[112:115], v[204:207], v[132:135]
	v_mfma_f32_16x16x32_bf16 v[128:131], v[124:127], v[204:207], v[128:131]
	v_mfma_f32_16x16x32_bf16 v[84:87], v[112:115], v[212:215], v[84:87]
	v_mfma_f32_16x16x32_bf16 v[80:83], v[124:127], v[212:215], v[80:83]
	s_barrier
	s_add_i32 s4, s68, s27
	v_lshl_add_u64 v[178:179], v[178:179], 0, s[82:83]
	s_mov_b32 m0, s4
	ds_read_b128 v[152:155], v251 offset:49152
	ds_read_b128 v[156:159], v251 offset:50176
	ds_read_b128 v[168:171], v251 offset:51200
	ds_read_b128 v[172:175], v251 offset:52224
	ds_read_b128 v[200:203], v251 offset:53248
	ds_read_b128 v[204:207], v251 offset:54272
	ds_read_b128 v[208:211], v251 offset:55296
	ds_read_b128 v[212:215], v251 offset:56320
	global_load_lds_dwordx4 v[178:179], off
	s_add_i32 m0, s4, 0x2000
	s_add_u32 s0, s0, 0x40080
	v_lshl_add_u64 v[178:179], v[180:181], 0, s[82:83]
	s_addc_u32 s1, s1, 0
	s_add_i32 s4, s69, s27
	global_load_lds_dwordx4 v[178:179], off
	s_mov_b32 m0, s4
	s_nop 0
	global_load_lds_dwordx4 v176, s[0:1]
	s_add_i32 m0, s4, 0x2000
	s_nop 0
	global_load_lds_dwordx4 v190, s[0:1]
	v_lshl_add_u64 v[178:179], v[186:187], 0, s[82:83]
	s_mov_b32 m0, s64
	s_nop 0
	global_load_lds_dwordx4 v[178:179], off
	v_lshl_add_u64 v[178:179], v[188:189], 0, s[82:83]
	s_mov_b32 m0, s65
	s_nop 0
	global_load_lds_dwordx4 v[178:179], off
	s_waitcnt vmcnt(8)
	s_waitcnt lgkmcnt(0)
	s_barrier
	s_waitcnt lgkmcnt(0)
	v_mfma_f32_16x16x32_bf16 v[76:79], v[56:59], v[152:155], v[76:79]
	v_mfma_f32_16x16x32_bf16 v[72:75], v[64:67], v[152:155], v[72:75]
	v_mfma_f32_16x16x32_bf16 v[52:55], v[56:59], v[168:171], v[52:55]
	v_mfma_f32_16x16x32_bf16 v[48:51], v[64:67], v[168:171], v[48:51]
	v_mfma_f32_16x16x32_bf16 v[28:31], v[56:59], v[200:203], v[28:31]
	v_mfma_f32_16x16x32_bf16 v[24:27], v[64:67], v[200:203], v[24:27]
	v_mfma_f32_16x16x32_bf16 v[12:15], v[56:59], v[208:211], v[12:15]
	v_mfma_f32_16x16x32_bf16 v[8:11], v[64:67], v[208:211], v[8:11]
	v_mfma_f32_16x16x32_bf16 v[76:79], v[60:63], v[156:159], v[76:79]
	v_mfma_f32_16x16x32_bf16 v[72:75], v[68:71], v[156:159], v[72:75]
	v_mfma_f32_16x16x32_bf16 v[52:55], v[60:63], v[172:175], v[52:55]
	v_mfma_f32_16x16x32_bf16 v[48:51], v[68:71], v[172:175], v[48:51]
	v_mfma_f32_16x16x32_bf16 v[28:31], v[60:63], v[204:207], v[28:31]
	v_mfma_f32_16x16x32_bf16 v[24:27], v[68:71], v[204:207], v[24:27]
	v_mfma_f32_16x16x32_bf16 v[12:15], v[60:63], v[212:215], v[12:15]
	v_mfma_f32_16x16x32_bf16 v[8:11], v[68:71], v[212:215], v[8:11]
	v_mfma_f32_16x16x32_bf16 v[40:43], v[104:107], v[152:155], v[40:43]
	v_mfma_f32_16x16x32_bf16 v[68:71], v[112:115], v[156:159], v[40:43]
	v_mfma_f32_16x16x32_bf16 v[40:43], v[120:123], v[152:155], v[44:47]
	v_mfma_f32_16x16x32_bf16 v[36:39], v[104:107], v[168:171], v[36:39]
	v_mfma_f32_16x16x32_bf16 v[32:35], v[120:123], v[168:171], v[32:35]
	v_mfma_f32_16x16x32_bf16 v[20:23], v[104:107], v[200:203], v[20:23]
	v_mfma_f32_16x16x32_bf16 v[16:19], v[120:123], v[200:203], v[16:19]
	v_mfma_f32_16x16x32_bf16 v[4:7], v[104:107], v[208:211], v[4:7]
	v_mfma_f32_16x16x32_bf16 v[0:3], v[120:123], v[208:211], v[0:3]
	v_mfma_f32_16x16x32_bf16 v[64:67], v[124:127], v[156:159], v[40:43]
	v_mfma_f32_16x16x32_bf16 v[36:39], v[112:115], v[172:175], v[36:39]
	v_mfma_f32_16x16x32_bf16 v[32:35], v[124:127], v[172:175], v[32:35]
	v_mfma_f32_16x16x32_bf16 v[20:23], v[112:115], v[204:207], v[20:23]
	v_mfma_f32_16x16x32_bf16 v[16:19], v[124:127], v[204:207], v[16:19]
	v_mfma_f32_16x16x32_bf16 v[4:7], v[112:115], v[212:215], v[4:7]
	v_mfma_f32_16x16x32_bf16 v[0:3], v[124:127], v[212:215], v[0:3]
	s_add_i32 s47, s47, 2
	s_add_u32 s40, s40, 0x100
	s_addc_u32 s41, s41, 0
	s_add_u32 s43, s43, 0x100
	s_addc_u32 s46, s46, 0
	s_cmp_gt_u32 s47, 13
	s_cbranch_scc0 .LBB0_108
	s_barrier
	s_and_b64 vcc, exec, s[30:31]
	s_cbranch_vccz .LBB0_111
	s_barrier

.LBB0_661:
	s_ashr_i32 s53, s52, 31
	s_lshl_b64 s[6:7], s[52:53], 19
	s_add_u32 s54, s12, s6
	s_addc_u32 s55, s20, s7
	s_and_b64 s[6:7], s[42:43], exec
	s_cselect_b32 s6, s55, s5
	s_cselect_b32 s7, s54, s4
	s_ashr_i32 s41, s40, 31
	s_lshl_b64 s[44:45], s[40:41], 19
	s_add_u32 s56, s27, s44
	s_addc_u32 s57, s60, s45
	s_and_b64 s[44:45], s[42:43], exec
	s_cselect_b32 s41, s57, s1
	s_cselect_b32 s53, s56, s0
	s_add_u32 s44, s4, 0x40080
	s_addc_u32 s45, s5, 0
	s_add_u32 s74, s0, 0x100
	v_mov_b32_e32 v0, 0
	s_addc_u32 s75, s1, 0
	s_mov_b32 s86, -2
	v_mov_b32_e32 v1, v0
	v_mov_b32_e32 v2, v0
	v_mov_b32_e32 v3, v0
	v_mov_b32_e32 v4, v0
	v_mov_b32_e32 v5, v0
	v_mov_b32_e32 v6, v0
	v_mov_b32_e32 v7, v0
	v_mov_b32_e32 v16, v0
	v_mov_b32_e32 v17, v0
	v_mov_b32_e32 v18, v0
	v_mov_b32_e32 v19, v0
	v_mov_b32_e32 v20, v0
	v_mov_b32_e32 v21, v0
	v_mov_b32_e32 v22, v0
	v_mov_b32_e32 v23, v0
	v_mov_b32_e32 v32, v0
	v_mov_b32_e32 v33, v0
	v_mov_b32_e32 v34, v0
	v_mov_b32_e32 v35, v0
	v_mov_b32_e32 v36, v0
	v_mov_b32_e32 v37, v0
	v_mov_b32_e32 v38, v0
	v_mov_b32_e32 v39, v0
	v_mov_b32_e32 v48, v0
	v_mov_b32_e32 v49, v0
	v_mov_b32_e32 v50, v0
	v_mov_b32_e32 v51, v0
	v_mov_b32_e32 v52, v0
	v_mov_b32_e32 v53, v0
	v_mov_b32_e32 v54, v0
	v_mov_b32_e32 v55, v0
	v_mov_b32_e32 v8, v0
	v_mov_b32_e32 v9, v0
	v_mov_b32_e32 v10, v0
	v_mov_b32_e32 v11, v0
	v_mov_b32_e32 v12, v0
	v_mov_b32_e32 v13, v0
	v_mov_b32_e32 v14, v0
	v_mov_b32_e32 v15, v0
	v_mov_b32_e32 v24, v0
	v_mov_b32_e32 v25, v0
	v_mov_b32_e32 v26, v0
	v_mov_b32_e32 v27, v0
	v_mov_b32_e32 v28, v0
	v_mov_b32_e32 v29, v0
	v_mov_b32_e32 v30, v0
	v_mov_b32_e32 v31, v0
	v_mov_b32_e32 v40, v0
	v_mov_b32_e32 v41, v0
	v_mov_b32_e32 v42, v0
	v_mov_b32_e32 v43, v0
	v_mov_b32_e32 v44, v0
	v_mov_b32_e32 v45, v0
	v_mov_b32_e32 v46, v0
	v_mov_b32_e32 v47, v0
	v_mov_b32_e32 v56, v0
	v_mov_b32_e32 v57, v0
	v_mov_b32_e32 v58, v0
	v_mov_b32_e32 v59, v0
	v_mov_b32_e32 v60, v0
	v_mov_b32_e32 v61, v0
	v_mov_b32_e32 v62, v0
	v_mov_b32_e32 v63, v0
	v_mov_b32_e32 v64, v0
	v_mov_b32_e32 v65, v0
	v_mov_b32_e32 v66, v0
	v_mov_b32_e32 v67, v0
	v_mov_b32_e32 v68, v0
	v_mov_b32_e32 v69, v0
	v_mov_b32_e32 v70, v0
	v_mov_b32_e32 v71, v0
	v_mov_b32_e32 v80, v0
	v_mov_b32_e32 v81, v0
	v_mov_b32_e32 v82, v0
	v_mov_b32_e32 v83, v0
	v_mov_b32_e32 v84, v0
	v_mov_b32_e32 v85, v0
	v_mov_b32_e32 v86, v0
	v_mov_b32_e32 v87, v0
	v_mov_b32_e32 v96, v0
	v_mov_b32_e32 v97, v0
	v_mov_b32_e32 v98, v0
	v_mov_b32_e32 v99, v0
	v_mov_b32_e32 v100, v0
	v_mov_b32_e32 v101, v0
	v_mov_b32_e32 v102, v0
	v_mov_b32_e32 v103, v0
	v_mov_b32_e32 v112, v0
	v_mov_b32_e32 v113, v0
	v_mov_b32_e32 v114, v0
	v_mov_b32_e32 v115, v0
	v_mov_b32_e32 v116, v0
	v_mov_b32_e32 v117, v0
	v_mov_b32_e32 v118, v0
	v_mov_b32_e32 v119, v0
	v_mov_b32_e32 v72, v0
	v_mov_b32_e32 v73, v0
	v_mov_b32_e32 v74, v0
	v_mov_b32_e32 v75, v0
	v_mov_b32_e32 v76, v0
	v_mov_b32_e32 v77, v0
	v_mov_b32_e32 v78, v0
	v_mov_b32_e32 v79, v0
	v_mov_b32_e32 v88, v0
	v_mov_b32_e32 v89, v0
	v_mov_b32_e32 v90, v0
	v_mov_b32_e32 v91, v0
	v_mov_b32_e32 v92, v0
	v_mov_b32_e32 v93, v0
	v_mov_b32_e32 v94, v0
	v_mov_b32_e32 v95, v0
	v_mov_b32_e32 v104, v0
	v_mov_b32_e32 v105, v0
	v_mov_b32_e32 v106, v0
	v_mov_b32_e32 v107, v0
	v_mov_b32_e32 v108, v0
	v_mov_b32_e32 v109, v0
	v_mov_b32_e32 v110, v0
	v_mov_b32_e32 v111, v0
	v_mov_b32_e32 v120, v0
	v_mov_b32_e32 v121, v0
	v_mov_b32_e32 v122, v0
	v_mov_b32_e32 v123, v0
	v_mov_b32_e32 v124, v0
	v_mov_b32_e32 v125, v0
	v_mov_b32_e32 v126, v0
	v_mov_b32_e32 v127, v0
	s_add_u32 s0, s44, 0xfffc0080
	s_addc_u32 s1, s45, -1
	s_add_i32 s87, 0, 0x10000
	s_cmp_eq_u32 s86, 12
	s_cselect_b32 s5, s6, s1
	s_cselect_b32 s4, s7, s0
	s_cselect_b32 s1, s41, s75
	s_cselect_b32 s0, s53, s74
	s_add_i32 s90, 0, 0x14000
	s_branch .Lrot_body_662
.LBB0_662:
	s_add_u32 s0, s44, 0xfffc0080
	s_addc_u32 s1, s45, -1
	s_add_i32 s87, 0, 0x10000
	s_cmp_eq_u32 s86, 12
	s_cselect_b32 s5, s6, s1
	s_cselect_b32 s4, s7, s0
	s_cselect_b32 s1, s41, s75
	s_cselect_b32 s0, s53, s74
	s_add_i32 s90, 0, 0x14000
	s_barrier
.Lrot_body_662:
	v_add_u32_e32 v140, s87, v162
	v_add_u32_e32 v168, s90, v162
	ds_read_b128 v[128:131], v140
	ds_read_b128 v[132:135], v140 offset:1024
	ds_read_b128 v[136:139], v140 offset:2048
	ds_read_b128 v[140:143], v140 offset:3072
	ds_read_b128 v[154:157], v168
	ds_read_b128 v[158:161], v168 offset:1024
	ds_read_b128 v[164:167], v168 offset:2048
	ds_read_b128 v[168:171], v168 offset:3072
	s_add_i32 m0, s62, 0xc000
	ds_read_b128 v[172:175], v163
	ds_read_b128 v[178:181], v163 offset:1024
	ds_read_b128 v[186:189], v163 offset:2048
	ds_read_b128 v[190:193], v163 offset:3072
	ds_read_b128 v[194:197], v163 offset:4096
	ds_read_b128 v[198:201], v163 offset:5120
	ds_read_b128 v[202:205], v163 offset:6144
	ds_read_b128 v[206:209], v163 offset:7168
	global_load_lds_dwordx4 v150, s[44:45]
	s_add_i32 m0, s62, 0xe000
	s_nop 0
	global_load_lds_dwordx4 v152, s[44:45]
	s_waitcnt vmcnt(8)
	s_waitcnt lgkmcnt(0)
	s_barrier
	s_waitcnt lgkmcnt(0)
	v_mfma_f32_16x16x32_bf16 v[124:127], v[128:131], v[172:175], v[124:127]
	v_mfma_f32_16x16x32_bf16 v[120:123], v[136:139], v[172:175], v[120:123]
	v_mfma_f32_16x16x32_bf16 v[108:111], v[128:131], v[186:189], v[108:111]
	v_mfma_f32_16x16x32_bf16 v[104:107], v[136:139], v[186:189], v[104:107]
	v_mfma_f32_16x16x32_bf16 v[92:95], v[128:131], v[194:197], v[92:95]
	v_mfma_f32_16x16x32_bf16 v[88:91], v[136:139], v[194:197], v[88:91]
	v_mfma_f32_16x16x32_bf16 v[76:79], v[128:131], v[202:205], v[76:79]
	v_mfma_f32_16x16x32_bf16 v[72:75], v[136:139], v[202:205], v[72:75]
	v_mfma_f32_16x16x32_bf16 v[124:127], v[132:135], v[178:181], v[124:127]
	v_mfma_f32_16x16x32_bf16 v[120:123], v[140:143], v[178:181], v[120:123]
	v_mfma_f32_16x16x32_bf16 v[108:111], v[132:135], v[190:193], v[108:111]
	v_mfma_f32_16x16x32_bf16 v[104:107], v[140:143], v[190:193], v[104:107]
	v_mfma_f32_16x16x32_bf16 v[92:95], v[132:135], v[198:201], v[92:95]
	v_mfma_f32_16x16x32_bf16 v[88:91], v[140:143], v[198:201], v[88:91]
	v_mfma_f32_16x16x32_bf16 v[76:79], v[132:135], v[206:209], v[76:79]
	v_mfma_f32_16x16x32_bf16 v[72:75], v[140:143], v[206:209], v[72:75]
	v_mfma_f32_16x16x32_bf16 v[116:119], v[154:157], v[172:175], v[116:119]
	v_mfma_f32_16x16x32_bf16 v[112:115], v[164:167], v[172:175], v[112:115]
	v_mfma_f32_16x16x32_bf16 v[100:103], v[154:157], v[186:189], v[100:103]
	v_mfma_f32_16x16x32_bf16 v[96:99], v[164:167], v[186:189], v[96:99]
	v_mfma_f32_16x16x32_bf16 v[84:87], v[154:157], v[194:197], v[84:87]
	v_mfma_f32_16x16x32_bf16 v[80:83], v[164:167], v[194:197], v[80:83]
	v_mfma_f32_16x16x32_bf16 v[68:71], v[154:157], v[202:205], v[68:71]
	v_mfma_f32_16x16x32_bf16 v[64:67], v[164:167], v[202:205], v[64:67]
	v_mfma_f32_16x16x32_bf16 v[116:119], v[158:161], v[178:181], v[116:119]
	v_mfma_f32_16x16x32_bf16 v[112:115], v[168:171], v[178:181], v[112:115]
	v_mfma_f32_16x16x32_bf16 v[100:103], v[158:161], v[190:193], v[100:103]
	v_mfma_f32_16x16x32_bf16 v[96:99], v[168:171], v[190:193], v[96:99]
	v_mfma_f32_16x16x32_bf16 v[84:87], v[158:161], v[198:201], v[84:87]
	v_mfma_f32_16x16x32_bf16 v[80:83], v[168:171], v[198:201], v[80:83]
	v_mfma_f32_16x16x32_bf16 v[68:71], v[158:161], v[206:209], v[68:71]
	v_mfma_f32_16x16x32_bf16 v[64:67], v[168:171], v[206:209], v[64:67]
	s_barrier
	s_add_i32 s87, s87, s61
	v_lshl_add_u64 v[182:183], s[0:1], 0, v[176:177]
	s_mov_b32 m0, s87
	ds_read_b128 v[172:175], v163 offset:16384
	ds_read_b128 v[178:181], v163 offset:17408
	ds_read_b128 v[186:189], v163 offset:18432
	ds_read_b128 v[190:193], v163 offset:19456
	ds_read_b128 v[194:197], v163 offset:20480
	ds_read_b128 v[198:201], v163 offset:21504
	ds_read_b128 v[202:205], v163 offset:22528
	ds_read_b128 v[206:209], v163 offset:23552
	global_load_lds_dwordx4 v176, s[0:1]
	s_add_i32 m0, s87, 0x2000
	s_add_u32 s88, s0, 0x40000
	v_lshl_add_u64 v[210:211], s[0:1], 0, v[144:145]
	s_addc_u32 s89, s1, 0
	s_add_i32 s87, s90, s61
	global_load_lds_dwordx4 v144, s[0:1]
	s_mov_b32 m0, s87
	v_lshl_add_u64 v[214:215], s[4:5], 0, v[146:147]
	global_load_lds_dwordx4 v176, s[88:89]
	s_add_i32 m0, s87, 0x2000
	s_nop 0
	global_load_lds_dwordx4 v144, s[88:89]
	v_lshl_add_u64 v[212:213], s[4:5], 0, v[148:149]
	s_mov_b32 m0, s62
	s_nop 0
	global_load_lds_dwordx4 v148, s[4:5]
	s_mov_b32 m0, s63
	s_nop 0
	global_load_lds_dwordx4 v146, s[4:5]
	s_waitcnt vmcnt(8)
	s_waitcnt lgkmcnt(0)
	s_barrier
	s_waitcnt lgkmcnt(0)
	v_mfma_f32_16x16x32_bf16 v[60:63], v[128:131], v[172:175], v[60:63]
	v_mfma_f32_16x16x32_bf16 v[56:59], v[136:139], v[172:175], v[56:59]
	v_mfma_f32_16x16x32_bf16 v[44:47], v[128:131], v[186:189], v[44:47]
	v_mfma_f32_16x16x32_bf16 v[40:43], v[136:139], v[186:189], v[40:43]
	v_mfma_f32_16x16x32_bf16 v[28:31], v[128:131], v[194:197], v[28:31]
	v_mfma_f32_16x16x32_bf16 v[24:27], v[136:139], v[194:197], v[24:27]
	v_mfma_f32_16x16x32_bf16 v[12:15], v[128:131], v[202:205], v[12:15]
	v_mfma_f32_16x16x32_bf16 v[8:11], v[136:139], v[202:205], v[8:11]
	v_mfma_f32_16x16x32_bf16 v[60:63], v[132:135], v[178:181], v[60:63]
	v_mfma_f32_16x16x32_bf16 v[56:59], v[140:143], v[178:181], v[56:59]
	v_mfma_f32_16x16x32_bf16 v[44:47], v[132:135], v[190:193], v[44:47]
	v_mfma_f32_16x16x32_bf16 v[40:43], v[140:143], v[190:193], v[40:43]
	v_mfma_f32_16x16x32_bf16 v[28:31], v[132:135], v[198:201], v[28:31]
	v_mfma_f32_16x16x32_bf16 v[24:27], v[140:143], v[198:201], v[24:27]
	v_mfma_f32_16x16x32_bf16 v[12:15], v[132:135], v[206:209], v[12:15]
	v_mfma_f32_16x16x32_bf16 v[8:11], v[140:143], v[206:209], v[8:11]
	v_mfma_f32_16x16x32_bf16 v[52:55], v[154:157], v[172:175], v[52:55]
	v_mfma_f32_16x16x32_bf16 v[48:51], v[164:167], v[172:175], v[48:51]
	v_mfma_f32_16x16x32_bf16 v[36:39], v[154:157], v[186:189], v[36:39]
	v_mfma_f32_16x16x32_bf16 v[32:35], v[164:167], v[186:189], v[32:35]
	v_mfma_f32_16x16x32_bf16 v[20:23], v[154:157], v[194:197], v[20:23]
	v_mfma_f32_16x16x32_bf16 v[16:19], v[164:167], v[194:197], v[16:19]
	v_mfma_f32_16x16x32_bf16 v[4:7], v[154:157], v[202:205], v[4:7]
	v_mfma_f32_16x16x32_bf16 v[0:3], v[164:167], v[202:205], v[0:3]
	v_mfma_f32_16x16x32_bf16 v[52:55], v[158:161], v[178:181], v[52:55]
	v_mfma_f32_16x16x32_bf16 v[48:51], v[168:171], v[178:181], v[48:51]
	v_mfma_f32_16x16x32_bf16 v[36:39], v[158:161], v[190:193], v[36:39]
	v_mfma_f32_16x16x32_bf16 v[32:35], v[168:171], v[190:193], v[32:35]
	v_mfma_f32_16x16x32_bf16 v[20:23], v[158:161], v[198:201], v[20:23]
	v_mfma_f32_16x16x32_bf16 v[16:19], v[168:171], v[198:201], v[16:19]
	v_mfma_f32_16x16x32_bf16 v[4:7], v[158:161], v[206:209], v[4:7]
	v_mfma_f32_16x16x32_bf16 v[0:3], v[168:171], v[206:209], v[0:3]
	s_barrier
	s_add_i32 s87, 0, 0x18000
	s_add_i32 s88, 0, 0x1c000
	v_add_u32_e32 v140, s87, v162
	v_add_u32_e32 v168, s88, v162
	ds_read_b128 v[128:131], v140
	ds_read_b128 v[132:135], v140 offset:1024
	ds_read_b128 v[136:139], v140 offset:2048
	ds_read_b128 v[140:143], v140 offset:3072
	ds_read_b128 v[154:157], v168
	ds_read_b128 v[158:161], v168 offset:1024
	ds_read_b128 v[164:167], v168 offset:2048
	ds_read_b128 v[168:171], v168 offset:3072
	s_add_u32 s4, s4, 0x40000
	s_addc_u32 s5, s5, 0
	s_mov_b32 m0, s64
	ds_read_b128 v[172:175], v163 offset:32768
	ds_read_b128 v[178:181], v163 offset:33792
	ds_read_b128 v[186:189], v163 offset:34816
	ds_read_b128 v[190:193], v163 offset:35840
	ds_read_b128 v[194:197], v163 offset:36864
	ds_read_b128 v[198:201], v163 offset:37888
	ds_read_b128 v[202:205], v163 offset:38912
	ds_read_b128 v[206:209], v163 offset:39936
	global_load_lds_dwordx4 v148, s[4:5]
	s_mov_b32 m0, s65
	s_nop 0
	global_load_lds_dwordx4 v146, s[4:5]
	s_waitcnt vmcnt(8)
	s_waitcnt lgkmcnt(0)
	s_barrier
	s_waitcnt lgkmcnt(0)
	v_mfma_f32_16x16x32_bf16 v[124:127], v[128:131], v[172:175], v[124:127]
	v_mfma_f32_16x16x32_bf16 v[120:123], v[136:139], v[172:175], v[120:123]
	v_mfma_f32_16x16x32_bf16 v[108:111], v[128:131], v[186:189], v[108:111]
	v_mfma_f32_16x16x32_bf16 v[104:107], v[136:139], v[186:189], v[104:107]
	v_mfma_f32_16x16x32_bf16 v[92:95], v[128:131], v[194:197], v[92:95]
	v_mfma_f32_16x16x32_bf16 v[88:91], v[136:139], v[194:197], v[88:91]
	v_mfma_f32_16x16x32_bf16 v[76:79], v[128:131], v[202:205], v[76:79]
	v_mfma_f32_16x16x32_bf16 v[72:75], v[136:139], v[202:205], v[72:75]
	v_mfma_f32_16x16x32_bf16 v[124:127], v[132:135], v[178:181], v[124:127]
	v_mfma_f32_16x16x32_bf16 v[120:123], v[140:143], v[178:181], v[120:123]
	v_mfma_f32_16x16x32_bf16 v[108:111], v[132:135], v[190:193], v[108:111]
	v_mfma_f32_16x16x32_bf16 v[104:107], v[140:143], v[190:193], v[104:107]
	v_mfma_f32_16x16x32_bf16 v[92:95], v[132:135], v[198:201], v[92:95]
	v_mfma_f32_16x16x32_bf16 v[88:91], v[140:143], v[198:201], v[88:91]
	v_mfma_f32_16x16x32_bf16 v[76:79], v[132:135], v[206:209], v[76:79]
	v_mfma_f32_16x16x32_bf16 v[72:75], v[140:143], v[206:209], v[72:75]
	v_mfma_f32_16x16x32_bf16 v[116:119], v[154:157], v[172:175], v[116:119]
	v_mfma_f32_16x16x32_bf16 v[112:115], v[164:167], v[172:175], v[112:115]
	v_mfma_f32_16x16x32_bf16 v[100:103], v[154:157], v[186:189], v[100:103]
	v_mfma_f32_16x16x32_bf16 v[96:99], v[164:167], v[186:189], v[96:99]
	v_mfma_f32_16x16x32_bf16 v[84:87], v[154:157], v[194:197], v[84:87]
	v_mfma_f32_16x16x32_bf16 v[80:83], v[164:167], v[194:197], v[80:83]
	v_mfma_f32_16x16x32_bf16 v[68:71], v[154:157], v[202:205], v[68:71]
	v_mfma_f32_16x16x32_bf16 v[64:67], v[164:167], v[202:205], v[64:67]
	v_mfma_f32_16x16x32_bf16 v[116:119], v[158:161], v[178:181], v[116:119]
	v_mfma_f32_16x16x32_bf16 v[112:115], v[168:171], v[178:181], v[112:115]
	v_mfma_f32_16x16x32_bf16 v[100:103], v[158:161], v[190:193], v[100:103]
	v_mfma_f32_16x16x32_bf16 v[96:99], v[168:171], v[190:193], v[96:99]
	v_mfma_f32_16x16x32_bf16 v[84:87], v[158:161], v[198:201], v[84:87]
	v_mfma_f32_16x16x32_bf16 v[80:83], v[168:171], v[198:201], v[80:83]
	v_mfma_f32_16x16x32_bf16 v[68:71], v[158:161], v[206:209], v[68:71]
	v_mfma_f32_16x16x32_bf16 v[64:67], v[168:171], v[206:209], v[64:67]
	s_barrier
	s_add_i32 s4, s87, s61
	v_lshl_add_u64 v[182:183], v[182:183], 0, s[82:83]
	s_mov_b32 m0, s4
	ds_read_b128 v[172:175], v163 offset:49152
	ds_read_b128 v[178:181], v163 offset:50176
	ds_read_b128 v[186:189], v163 offset:51200
	ds_read_b128 v[190:193], v163 offset:52224
	ds_read_b128 v[194:197], v163 offset:53248
	ds_read_b128 v[198:201], v163 offset:54272
	ds_read_b128 v[202:205], v163 offset:55296
	ds_read_b128 v[206:209], v163 offset:56320
	global_load_lds_dwordx4 v[182:183], off
	s_add_i32 m0, s4, 0x2000
	s_add_u32 s0, s0, 0x40080
	v_lshl_add_u64 v[182:183], v[210:211], 0, s[82:83]
	s_addc_u32 s1, s1, 0
	s_add_i32 s4, s88, s61
	global_load_lds_dwordx4 v[182:183], off
	s_mov_b32 m0, s4
	s_nop 0
	global_load_lds_dwordx4 v176, s[0:1]
	s_add_i32 m0, s4, 0x2000
	s_nop 0
	global_load_lds_dwordx4 v144, s[0:1]
	v_lshl_add_u64 v[182:183], v[212:213], 0, s[82:83]
	s_mov_b32 m0, s69
	s_nop 0
	global_load_lds_dwordx4 v[182:183], off
	v_lshl_add_u64 v[182:183], v[214:215], 0, s[82:83]
	s_mov_b32 m0, s70
	s_nop 0
	global_load_lds_dwordx4 v[182:183], off
	s_waitcnt vmcnt(8)
	s_waitcnt lgkmcnt(0)
	s_barrier
	s_waitcnt lgkmcnt(0)
	v_mfma_f32_16x16x32_bf16 v[60:63], v[128:131], v[172:175], v[60:63]
	v_mfma_f32_16x16x32_bf16 v[56:59], v[136:139], v[172:175], v[56:59]
	v_mfma_f32_16x16x32_bf16 v[44:47], v[128:131], v[186:189], v[44:47]
	v_mfma_f32_16x16x32_bf16 v[40:43], v[136:139], v[186:189], v[40:43]
	v_mfma_f32_16x16x32_bf16 v[28:31], v[128:131], v[194:197], v[28:31]
	v_mfma_f32_16x16x32_bf16 v[24:27], v[136:139], v[194:197], v[24:27]
	v_mfma_f32_16x16x32_bf16 v[12:15], v[128:131], v[202:205], v[12:15]
	v_mfma_f32_16x16x32_bf16 v[8:11], v[136:139], v[202:205], v[8:11]
	v_mfma_f32_16x16x32_bf16 v[60:63], v[132:135], v[178:181], v[60:63]
	v_mfma_f32_16x16x32_bf16 v[56:59], v[140:143], v[178:181], v[56:59]
	v_mfma_f32_16x16x32_bf16 v[44:47], v[132:135], v[190:193], v[44:47]
	v_mfma_f32_16x16x32_bf16 v[40:43], v[140:143], v[190:193], v[40:43]
	v_mfma_f32_16x16x32_bf16 v[28:31], v[132:135], v[198:201], v[28:31]
	v_mfma_f32_16x16x32_bf16 v[24:27], v[140:143], v[198:201], v[24:27]
	v_mfma_f32_16x16x32_bf16 v[12:15], v[132:135], v[206:209], v[12:15]
	v_mfma_f32_16x16x32_bf16 v[8:11], v[140:143], v[206:209], v[8:11]
	v_mfma_f32_16x16x32_bf16 v[52:55], v[154:157], v[172:175], v[52:55]
	v_mfma_f32_16x16x32_bf16 v[48:51], v[164:167], v[172:175], v[48:51]
	v_mfma_f32_16x16x32_bf16 v[36:39], v[154:157], v[186:189], v[36:39]
	v_mfma_f32_16x16x32_bf16 v[32:35], v[164:167], v[186:189], v[32:35]
	v_mfma_f32_16x16x32_bf16 v[20:23], v[154:157], v[194:197], v[20:23]
	v_mfma_f32_16x16x32_bf16 v[16:19], v[164:167], v[194:197], v[16:19]
	v_mfma_f32_16x16x32_bf16 v[4:7], v[154:157], v[202:205], v[4:7]
	v_mfma_f32_16x16x32_bf16 v[0:3], v[164:167], v[202:205], v[0:3]
	v_mfma_f32_16x16x32_bf16 v[52:55], v[158:161], v[178:181], v[52:55]
	v_mfma_f32_16x16x32_bf16 v[48:51], v[168:171], v[178:181], v[48:51]
	v_mfma_f32_16x16x32_bf16 v[36:39], v[158:161], v[190:193], v[36:39]
	v_mfma_f32_16x16x32_bf16 v[32:35], v[168:171], v[190:193], v[32:35]
	v_mfma_f32_16x16x32_bf16 v[20:23], v[158:161], v[198:201], v[20:23]
	v_mfma_f32_16x16x32_bf16 v[16:19], v[168:171], v[198:201], v[16:19]
	v_mfma_f32_16x16x32_bf16 v[4:7], v[158:161], v[206:209], v[4:7]
	v_mfma_f32_16x16x32_bf16 v[0:3], v[168:171], v[206:209], v[0:3]
	s_add_i32 s86, s86, 2
	s_add_u32 s44, s44, 0x100
	s_addc_u32 s45, s45, 0
	s_add_u32 s74, s74, 0x100
	s_addc_u32 s75, s75, 0
	s_cmp_gt_u32 s86, 13
	s_cbranch_scc0 .LBB0_662
	s_barrier
	s_and_b64 vcc, exec, s[38:39]
	s_cbranch_vccz .LBB0_665
	s_barrier

.LBB0_747:
	s_ashr_i32 s39, s38, 31
	s_lshl_b64 s[6:7], s[38:39], 19
	s_add_u32 s88, s12, s6
	s_addc_u32 s89, s20, s7
	s_and_b64 s[6:7], s[42:43], exec
	s_cselect_b32 s6, s89, s5
	s_cselect_b32 s7, s88, s4
	s_ashr_i32 s41, s40, 31
	s_lshl_b64 s[44:45], s[40:41], 19
	s_add_u32 s86, s27, s44
	s_addc_u32 s87, s60, s45
	s_and_b64 s[44:45], s[42:43], exec
	s_cselect_b32 s39, s87, s1
	s_cselect_b32 s41, s86, s0
	s_add_u32 s44, s4, 0x40080
	s_addc_u32 s45, s5, 0
	s_add_u32 s49, s0, 0x100
	s_addc_u32 s72, s1, 0
	s_mov_b32 s73, -2
	s_cmp_eq_u32 s71, 1
	s_cbranch_scc0 .Lpeel_748
	v_mov_b32_e32 v0, 0
	v_mov_b32_e32 v1, v0
	v_mov_b32_e32 v2, v0
	v_mov_b32_e32 v3, v0
	v_mov_b32_e32 v8, v0
	v_mov_b32_e32 v9, v0
	v_mov_b32_e32 v10, v0
	v_mov_b32_e32 v11, v0
	v_mov_b32_e32 v16, v0
	v_mov_b32_e32 v17, v0
	v_mov_b32_e32 v18, v0
	v_mov_b32_e32 v19, v0
	v_mov_b32_e32 v24, v0
	v_mov_b32_e32 v25, v0
	v_mov_b32_e32 v26, v0
	v_mov_b32_e32 v27, v0
	v_mov_b32_e32 v32, v0
	v_mov_b32_e32 v33, v0
	v_mov_b32_e32 v34, v0
	v_mov_b32_e32 v35, v0
	v_mov_b32_e32 v40, v0
	v_mov_b32_e32 v41, v0
	v_mov_b32_e32 v42, v0
	v_mov_b32_e32 v43, v0
	v_mov_b32_e32 v48, v0
	v_mov_b32_e32 v49, v0
	v_mov_b32_e32 v50, v0
	v_mov_b32_e32 v51, v0
	v_mov_b32_e32 v52, v0
	v_mov_b32_e32 v53, v0
	v_mov_b32_e32 v54, v0
	v_mov_b32_e32 v55, v0
	v_mov_b32_e32 v4, v0
	v_mov_b32_e32 v5, v0
	v_mov_b32_e32 v6, v0
	v_mov_b32_e32 v7, v0
	v_mov_b32_e32 v12, v0
	v_mov_b32_e32 v13, v0
	v_mov_b32_e32 v14, v0
	v_mov_b32_e32 v15, v0
	v_mov_b32_e32 v20, v0
	v_mov_b32_e32 v21, v0
	v_mov_b32_e32 v22, v0
	v_mov_b32_e32 v23, v0
	v_mov_b32_e32 v28, v0
	v_mov_b32_e32 v29, v0
	v_mov_b32_e32 v30, v0
	v_mov_b32_e32 v31, v0
	v_mov_b32_e32 v36, v0
	v_mov_b32_e32 v37, v0
	v_mov_b32_e32 v38, v0
	v_mov_b32_e32 v39, v0
	v_mov_b32_e32 v44, v0
	v_mov_b32_e32 v45, v0
	v_mov_b32_e32 v46, v0
	v_mov_b32_e32 v47, v0
	v_mov_b32_e32 v56, v0
	v_mov_b32_e32 v57, v0
	v_mov_b32_e32 v58, v0
	v_mov_b32_e32 v59, v0
	v_mov_b32_e32 v60, v0
	v_mov_b32_e32 v61, v0
	v_mov_b32_e32 v62, v0
	v_mov_b32_e32 v63, v0
	v_mov_b32_e32 v64, v0
	v_mov_b32_e32 v65, v0
	v_mov_b32_e32 v66, v0
	v_mov_b32_e32 v67, v0
	v_mov_b32_e32 v72, v0
	v_mov_b32_e32 v73, v0
	v_mov_b32_e32 v74, v0
	v_mov_b32_e32 v75, v0
	v_mov_b32_e32 v80, v0
	v_mov_b32_e32 v81, v0
	v_mov_b32_e32 v82, v0
	v_mov_b32_e32 v83, v0
	v_mov_b32_e32 v88, v0
	v_mov_b32_e32 v89, v0
	v_mov_b32_e32 v90, v0
	v_mov_b32_e32 v91, v0
	v_mov_b32_e32 v96, v0
	v_mov_b32_e32 v97, v0
	v_mov_b32_e32 v98, v0
	v_mov_b32_e32 v99, v0
	v_mov_b32_e32 v104, v0
	v_mov_b32_e32 v105, v0
	v_mov_b32_e32 v106, v0
	v_mov_b32_e32 v107, v0
	v_mov_b32_e32 v144, v0
	v_mov_b32_e32 v145, v0
	v_mov_b32_e32 v146, v0
	v_mov_b32_e32 v147, v0
	v_mov_b32_e32 v148, v0
	v_mov_b32_e32 v149, v0
	v_mov_b32_e32 v150, v0
	v_mov_b32_e32 v151, v0
	v_mov_b32_e32 v68, v0
	v_mov_b32_e32 v69, v0
	v_mov_b32_e32 v70, v0
	v_mov_b32_e32 v71, v0
	v_mov_b32_e32 v76, v0
	v_mov_b32_e32 v77, v0
	v_mov_b32_e32 v78, v0
	v_mov_b32_e32 v79, v0
	v_mov_b32_e32 v84, v0
	v_mov_b32_e32 v85, v0
	v_mov_b32_e32 v86, v0
	v_mov_b32_e32 v87, v0
	v_mov_b32_e32 v92, v0
	v_mov_b32_e32 v93, v0
	v_mov_b32_e32 v94, v0
	v_mov_b32_e32 v95, v0
	v_mov_b32_e32 v100, v0
	v_mov_b32_e32 v101, v0
	v_mov_b32_e32 v102, v0
	v_mov_b32_e32 v103, v0
	v_mov_b32_e32 v108, v0
	v_mov_b32_e32 v109, v0
	v_mov_b32_e32 v110, v0
	v_mov_b32_e32 v111, v0
	v_mov_b32_e32 v152, v0
	v_mov_b32_e32 v153, v0
	v_mov_b32_e32 v154, v0
	v_mov_b32_e32 v155, v0
	v_mov_b32_e32 v156, v0
	v_mov_b32_e32 v157, v0
	v_mov_b32_e32 v158, v0
	v_mov_b32_e32 v159, v0
	s_waitcnt vmcnt(0)
	s_add_u32 s0, s44, 0xfffc0080
	s_addc_u32 s1, s45, -1
	s_add_i32 s74, 0, 0x10000
	s_cmp_eq_u32 s73, 12
	s_cselect_b32 s5, s6, s1
	s_cselect_b32 s4, s7, s0
	s_cselect_b32 s1, s39, s72
	s_cselect_b32 s0, s41, s49
	s_add_i32 s92, 0, 0x14000
	s_branch .Lrot_body_748
.Lpeel_748:
	s_add_u32 s0, s44, 0xfffc0080
	s_addc_u32 s1, s45, -1
	s_add_i32 s74, 0, 0x10000
	s_cmp_eq_u32 s73, 12
	s_cselect_b32 s5, s6, s1
	s_cselect_b32 s4, s7, s0
	s_cselect_b32 s1, s39, s72
	s_cselect_b32 s0, s41, s49
	s_add_i32 s92, 0, 0x14000
	v_add_u32_e32 v124, s74, v199
	v_add_u32_e32 v140, s92, v199
	ds_read_b128 v[112:115], v124
	ds_read_b128 v[116:119], v124 offset:1024
	ds_read_b128 v[120:123], v124 offset:2048
	ds_read_b128 v[124:127], v124 offset:3072
	ds_read_b128 v[128:131], v140
	ds_read_b128 v[132:135], v140 offset:1024
	ds_read_b128 v[136:139], v140 offset:2048
	ds_read_b128 v[140:143], v140 offset:3072
	s_add_i32 m0, s63, 0xc000
	ds_read_b128 v[172:175], v207
	ds_read_b128 v[178:181], v207 offset:1024
	ds_read_b128 v[186:189], v207 offset:2048
	ds_read_b128 v[190:193], v207 offset:3072
	ds_read_b128 v[194:197], v207 offset:4096
	ds_read_b128 v[200:203], v207 offset:5120
	ds_read_b128 v[208:211], v207 offset:6144
	ds_read_b128 v[212:215], v207 offset:7168
	global_load_lds_dwordx4 v168, s[44:45]
	s_add_i32 m0, s63, 0xe000
	s_nop 0
	global_load_lds_dwordx4 v170, s[44:45]
	s_waitcnt vmcnt(8)
	s_waitcnt lgkmcnt(0)
	s_barrier
	s_waitcnt lgkmcnt(0)
	v_mfma_f32_16x16x32_bf16 v[156:159], v[112:115], v[172:175], 0
	v_mfma_f32_16x16x32_bf16 v[152:155], v[120:123], v[172:175], 0
	v_mfma_f32_16x16x32_bf16 v[108:111], v[112:115], v[186:189], 0
	v_mfma_f32_16x16x32_bf16 v[100:103], v[120:123], v[186:189], 0
	v_mfma_f32_16x16x32_bf16 v[92:95], v[112:115], v[194:197], 0
	v_mfma_f32_16x16x32_bf16 v[84:87], v[120:123], v[194:197], 0
	v_mfma_f32_16x16x32_bf16 v[76:79], v[112:115], v[208:211], 0
	v_mfma_f32_16x16x32_bf16 v[68:71], v[120:123], v[208:211], 0
	v_mfma_f32_16x16x32_bf16 v[156:159], v[116:119], v[178:181], v[156:159]
	v_mfma_f32_16x16x32_bf16 v[152:155], v[124:127], v[178:181], v[152:155]
	v_mfma_f32_16x16x32_bf16 v[108:111], v[116:119], v[190:193], v[108:111]
	v_mfma_f32_16x16x32_bf16 v[100:103], v[124:127], v[190:193], v[100:103]
	v_mfma_f32_16x16x32_bf16 v[92:95], v[116:119], v[200:203], v[92:95]
	v_mfma_f32_16x16x32_bf16 v[84:87], v[124:127], v[200:203], v[84:87]
	v_mfma_f32_16x16x32_bf16 v[76:79], v[116:119], v[212:215], v[76:79]
	v_mfma_f32_16x16x32_bf16 v[68:71], v[124:127], v[212:215], v[68:71]
	v_mfma_f32_16x16x32_bf16 v[148:151], v[128:131], v[172:175], 0
	v_mfma_f32_16x16x32_bf16 v[144:147], v[136:139], v[172:175], 0
	v_mfma_f32_16x16x32_bf16 v[104:107], v[128:131], v[186:189], 0
	v_mfma_f32_16x16x32_bf16 v[96:99], v[136:139], v[186:189], 0
	v_mfma_f32_16x16x32_bf16 v[88:91], v[128:131], v[194:197], 0
	v_mfma_f32_16x16x32_bf16 v[80:83], v[136:139], v[194:197], 0
	v_mfma_f32_16x16x32_bf16 v[72:75], v[128:131], v[208:211], 0
	v_mfma_f32_16x16x32_bf16 v[64:67], v[136:139], v[208:211], 0
	v_mfma_f32_16x16x32_bf16 v[148:151], v[132:135], v[178:181], v[148:151]
	v_mfma_f32_16x16x32_bf16 v[144:147], v[140:143], v[178:181], v[144:147]
	v_mfma_f32_16x16x32_bf16 v[104:107], v[132:135], v[190:193], v[104:107]
	v_mfma_f32_16x16x32_bf16 v[96:99], v[140:143], v[190:193], v[96:99]
	v_mfma_f32_16x16x32_bf16 v[88:91], v[132:135], v[200:203], v[88:91]
	v_mfma_f32_16x16x32_bf16 v[80:83], v[140:143], v[200:203], v[80:83]
	v_mfma_f32_16x16x32_bf16 v[72:75], v[132:135], v[212:215], v[72:75]
	v_mfma_f32_16x16x32_bf16 v[64:67], v[140:143], v[212:215], v[64:67]
	s_barrier
	s_add_i32 s74, s74, s62
	v_lshl_add_u64 v[182:183], s[0:1], 0, v[164:165]
	s_mov_b32 m0, s74
	ds_read_b128 v[172:175], v207 offset:16384
	ds_read_b128 v[178:181], v207 offset:17408
	ds_read_b128 v[186:189], v207 offset:18432
	ds_read_b128 v[190:193], v207 offset:19456
	ds_read_b128 v[194:197], v207 offset:20480
	ds_read_b128 v[200:203], v207 offset:21504
	ds_read_b128 v[208:211], v207 offset:22528
	ds_read_b128 v[212:215], v207 offset:23552
	global_load_lds_dwordx4 v164, s[0:1]
	s_add_i32 m0, s74, 0x2000
	s_add_u32 s74, s0, 0x40000
	v_lshl_add_u64 v[204:205], s[0:1], 0, v[160:161]
	s_addc_u32 s75, s1, 0
	s_add_i32 s92, s92, s62
	global_load_lds_dwordx4 v160, s[0:1]
	s_mov_b32 m0, s92
	v_lshl_add_u64 v[218:219], s[4:5], 0, v[162:163]
	global_load_lds_dwordx4 v164, s[74:75]
	s_add_i32 m0, s92, 0x2000
	s_nop 0
	global_load_lds_dwordx4 v160, s[74:75]
	v_lshl_add_u64 v[216:217], s[4:5], 0, v[166:167]
	s_mov_b32 m0, s63
	s_nop 0
	global_load_lds_dwordx4 v166, s[4:5]
	s_mov_b32 m0, s64
	s_nop 0
	global_load_lds_dwordx4 v162, s[4:5]
	s_waitcnt vmcnt(8)
	s_waitcnt lgkmcnt(0)
	s_barrier
	s_waitcnt lgkmcnt(0)
	v_mfma_f32_16x16x32_bf16 v[60:63], v[112:115], v[172:175], 0
	v_mfma_f32_16x16x32_bf16 v[56:59], v[120:123], v[172:175], 0
	v_mfma_f32_16x16x32_bf16 v[44:47], v[112:115], v[186:189], 0
	v_mfma_f32_16x16x32_bf16 v[36:39], v[120:123], v[186:189], 0
	v_mfma_f32_16x16x32_bf16 v[28:31], v[112:115], v[194:197], 0
	v_mfma_f32_16x16x32_bf16 v[20:23], v[120:123], v[194:197], 0
	v_mfma_f32_16x16x32_bf16 v[12:15], v[112:115], v[208:211], 0
	v_mfma_f32_16x16x32_bf16 v[4:7], v[120:123], v[208:211], 0
	v_mfma_f32_16x16x32_bf16 v[60:63], v[116:119], v[178:181], v[60:63]
	v_mfma_f32_16x16x32_bf16 v[56:59], v[124:127], v[178:181], v[56:59]
	v_mfma_f32_16x16x32_bf16 v[44:47], v[116:119], v[190:193], v[44:47]
	v_mfma_f32_16x16x32_bf16 v[36:39], v[124:127], v[190:193], v[36:39]
	v_mfma_f32_16x16x32_bf16 v[28:31], v[116:119], v[200:203], v[28:31]
	v_mfma_f32_16x16x32_bf16 v[20:23], v[124:127], v[200:203], v[20:23]
	v_mfma_f32_16x16x32_bf16 v[12:15], v[116:119], v[212:215], v[12:15]
	v_mfma_f32_16x16x32_bf16 v[4:7], v[124:127], v[212:215], v[4:7]
	v_mfma_f32_16x16x32_bf16 v[52:55], v[128:131], v[172:175], 0
	v_mfma_f32_16x16x32_bf16 v[48:51], v[136:139], v[172:175], 0
	v_mfma_f32_16x16x32_bf16 v[40:43], v[128:131], v[186:189], 0
	v_mfma_f32_16x16x32_bf16 v[32:35], v[136:139], v[186:189], 0
	v_mfma_f32_16x16x32_bf16 v[24:27], v[128:131], v[194:197], 0
	v_mfma_f32_16x16x32_bf16 v[16:19], v[136:139], v[194:197], 0
	v_mfma_f32_16x16x32_bf16 v[8:11], v[128:131], v[208:211], 0
	v_mfma_f32_16x16x32_bf16 v[0:3], v[136:139], v[208:211], 0
	v_mfma_f32_16x16x32_bf16 v[52:55], v[132:135], v[178:181], v[52:55]
	v_mfma_f32_16x16x32_bf16 v[48:51], v[140:143], v[178:181], v[48:51]
	v_mfma_f32_16x16x32_bf16 v[40:43], v[132:135], v[190:193], v[40:43]
	v_mfma_f32_16x16x32_bf16 v[32:35], v[140:143], v[190:193], v[32:35]
	v_mfma_f32_16x16x32_bf16 v[24:27], v[132:135], v[200:203], v[24:27]
	v_mfma_f32_16x16x32_bf16 v[16:19], v[140:143], v[200:203], v[16:19]
	v_mfma_f32_16x16x32_bf16 v[8:11], v[132:135], v[212:215], v[8:11]
	v_mfma_f32_16x16x32_bf16 v[0:3], v[140:143], v[212:215], v[0:3]
	s_barrier
	s_add_i32 s74, 0, 0x18000
	s_add_i32 s75, 0, 0x1c000
	v_add_u32_e32 v124, s74, v199
	v_add_u32_e32 v140, s75, v199
	ds_read_b128 v[112:115], v124
	ds_read_b128 v[116:119], v124 offset:1024
	ds_read_b128 v[120:123], v124 offset:2048
	ds_read_b128 v[124:127], v124 offset:3072
	ds_read_b128 v[128:131], v140
	ds_read_b128 v[132:135], v140 offset:1024
	ds_read_b128 v[136:139], v140 offset:2048
	ds_read_b128 v[140:143], v140 offset:3072
	s_add_u32 s4, s4, 0x40000
	s_addc_u32 s5, s5, 0
	s_mov_b32 m0, s65
	ds_read_b128 v[172:175], v207 offset:32768
	ds_read_b128 v[178:181], v207 offset:33792
	ds_read_b128 v[186:189], v207 offset:34816
	ds_read_b128 v[190:193], v207 offset:35840
	ds_read_b128 v[194:197], v207 offset:36864
	ds_read_b128 v[200:203], v207 offset:37888
	ds_read_b128 v[208:211], v207 offset:38912
	ds_read_b128 v[212:215], v207 offset:39936
	global_load_lds_dwordx4 v166, s[4:5]
	s_mov_b32 m0, s66
	s_nop 0
	global_load_lds_dwordx4 v162, s[4:5]
	s_waitcnt vmcnt(8)
	s_waitcnt lgkmcnt(0)
	s_barrier
	s_waitcnt lgkmcnt(0)
	v_mfma_f32_16x16x32_bf16 v[156:159], v[112:115], v[172:175], v[156:159]
	v_mfma_f32_16x16x32_bf16 v[152:155], v[120:123], v[172:175], v[152:155]
	v_mfma_f32_16x16x32_bf16 v[108:111], v[112:115], v[186:189], v[108:111]
	v_mfma_f32_16x16x32_bf16 v[100:103], v[120:123], v[186:189], v[100:103]
	v_mfma_f32_16x16x32_bf16 v[92:95], v[112:115], v[194:197], v[92:95]
	v_mfma_f32_16x16x32_bf16 v[84:87], v[120:123], v[194:197], v[84:87]
	v_mfma_f32_16x16x32_bf16 v[76:79], v[112:115], v[208:211], v[76:79]
	v_mfma_f32_16x16x32_bf16 v[68:71], v[120:123], v[208:211], v[68:71]
	v_mfma_f32_16x16x32_bf16 v[156:159], v[116:119], v[178:181], v[156:159]
	v_mfma_f32_16x16x32_bf16 v[152:155], v[124:127], v[178:181], v[152:155]
	v_mfma_f32_16x16x32_bf16 v[108:111], v[116:119], v[190:193], v[108:111]
	v_mfma_f32_16x16x32_bf16 v[100:103], v[124:127], v[190:193], v[100:103]
	v_mfma_f32_16x16x32_bf16 v[92:95], v[116:119], v[200:203], v[92:95]
	v_mfma_f32_16x16x32_bf16 v[84:87], v[124:127], v[200:203], v[84:87]
	v_mfma_f32_16x16x32_bf16 v[76:79], v[116:119], v[212:215], v[76:79]
	v_mfma_f32_16x16x32_bf16 v[68:71], v[124:127], v[212:215], v[68:71]
	v_mfma_f32_16x16x32_bf16 v[148:151], v[128:131], v[172:175], v[148:151]
	v_mfma_f32_16x16x32_bf16 v[144:147], v[136:139], v[172:175], v[144:147]
	v_mfma_f32_16x16x32_bf16 v[104:107], v[128:131], v[186:189], v[104:107]
	v_mfma_f32_16x16x32_bf16 v[96:99], v[136:139], v[186:189], v[96:99]
	v_mfma_f32_16x16x32_bf16 v[88:91], v[128:131], v[194:197], v[88:91]
	v_mfma_f32_16x16x32_bf16 v[80:83], v[136:139], v[194:197], v[80:83]
	v_mfma_f32_16x16x32_bf16 v[72:75], v[128:131], v[208:211], v[72:75]
	v_mfma_f32_16x16x32_bf16 v[64:67], v[136:139], v[208:211], v[64:67]
	v_mfma_f32_16x16x32_bf16 v[148:151], v[132:135], v[178:181], v[148:151]
	v_mfma_f32_16x16x32_bf16 v[144:147], v[140:143], v[178:181], v[144:147]
	v_mfma_f32_16x16x32_bf16 v[104:107], v[132:135], v[190:193], v[104:107]
	v_mfma_f32_16x16x32_bf16 v[96:99], v[140:143], v[190:193], v[96:99]
	v_mfma_f32_16x16x32_bf16 v[88:91], v[132:135], v[200:203], v[88:91]
	v_mfma_f32_16x16x32_bf16 v[80:83], v[140:143], v[200:203], v[80:83]
	v_mfma_f32_16x16x32_bf16 v[72:75], v[132:135], v[212:215], v[72:75]
	v_mfma_f32_16x16x32_bf16 v[64:67], v[140:143], v[212:215], v[64:67]
	s_barrier
	s_add_i32 s4, s74, s62
	v_lshl_add_u64 v[182:183], v[182:183], 0, s[82:83]
	s_mov_b32 m0, s4
	ds_read_b128 v[172:175], v207 offset:49152
	ds_read_b128 v[178:181], v207 offset:50176
	ds_read_b128 v[186:189], v207 offset:51200
	ds_read_b128 v[190:193], v207 offset:52224
	ds_read_b128 v[194:197], v207 offset:53248
	ds_read_b128 v[200:203], v207 offset:54272
	ds_read_b128 v[208:211], v207 offset:55296
	ds_read_b128 v[212:215], v207 offset:56320
	global_load_lds_dwordx4 v[182:183], off
	s_add_i32 m0, s4, 0x2000
	s_add_u32 s0, s0, 0x40080
	v_lshl_add_u64 v[182:183], v[204:205], 0, s[82:83]
	s_addc_u32 s1, s1, 0
	s_add_i32 s4, s75, s62
	global_load_lds_dwordx4 v[182:183], off
	s_mov_b32 m0, s4
	s_nop 0
	global_load_lds_dwordx4 v164, s[0:1]
	s_add_i32 m0, s4, 0x2000
	s_nop 0
	global_load_lds_dwordx4 v160, s[0:1]
	v_lshl_add_u64 v[182:183], v[216:217], 0, s[82:83]
	s_mov_b32 m0, s69
	s_nop 0
	global_load_lds_dwordx4 v[182:183], off
	v_lshl_add_u64 v[182:183], v[218:219], 0, s[82:83]
	s_mov_b32 m0, s70
	s_nop 0
	global_load_lds_dwordx4 v[182:183], off
	s_waitcnt vmcnt(8)
	s_waitcnt lgkmcnt(0)
	s_barrier
	s_waitcnt lgkmcnt(0)
	v_mfma_f32_16x16x32_bf16 v[60:63], v[112:115], v[172:175], v[60:63]
	v_mfma_f32_16x16x32_bf16 v[56:59], v[120:123], v[172:175], v[56:59]
	v_mfma_f32_16x16x32_bf16 v[44:47], v[112:115], v[186:189], v[44:47]
	v_mfma_f32_16x16x32_bf16 v[36:39], v[120:123], v[186:189], v[36:39]
	v_mfma_f32_16x16x32_bf16 v[28:31], v[112:115], v[194:197], v[28:31]
	v_mfma_f32_16x16x32_bf16 v[20:23], v[120:123], v[194:197], v[20:23]
	v_mfma_f32_16x16x32_bf16 v[12:15], v[112:115], v[208:211], v[12:15]
	v_mfma_f32_16x16x32_bf16 v[4:7], v[120:123], v[208:211], v[4:7]
	v_mfma_f32_16x16x32_bf16 v[60:63], v[116:119], v[178:181], v[60:63]
	v_mfma_f32_16x16x32_bf16 v[56:59], v[124:127], v[178:181], v[56:59]
	v_mfma_f32_16x16x32_bf16 v[44:47], v[116:119], v[190:193], v[44:47]
	v_mfma_f32_16x16x32_bf16 v[36:39], v[124:127], v[190:193], v[36:39]
	v_mfma_f32_16x16x32_bf16 v[28:31], v[116:119], v[200:203], v[28:31]
	v_mfma_f32_16x16x32_bf16 v[20:23], v[124:127], v[200:203], v[20:23]
	v_mfma_f32_16x16x32_bf16 v[12:15], v[116:119], v[212:215], v[12:15]
	v_mfma_f32_16x16x32_bf16 v[4:7], v[124:127], v[212:215], v[4:7]
	v_mfma_f32_16x16x32_bf16 v[52:55], v[128:131], v[172:175], v[52:55]
	v_mfma_f32_16x16x32_bf16 v[48:51], v[136:139], v[172:175], v[48:51]
	v_mfma_f32_16x16x32_bf16 v[40:43], v[128:131], v[186:189], v[40:43]
	v_mfma_f32_16x16x32_bf16 v[32:35], v[136:139], v[186:189], v[32:35]
	v_mfma_f32_16x16x32_bf16 v[24:27], v[128:131], v[194:197], v[24:27]
	v_mfma_f32_16x16x32_bf16 v[16:19], v[136:139], v[194:197], v[16:19]
	v_mfma_f32_16x16x32_bf16 v[8:11], v[128:131], v[208:211], v[8:11]
	v_mfma_f32_16x16x32_bf16 v[0:3], v[136:139], v[208:211], v[0:3]
	v_mfma_f32_16x16x32_bf16 v[52:55], v[132:135], v[178:181], v[52:55]
	v_mfma_f32_16x16x32_bf16 v[48:51], v[140:143], v[178:181], v[48:51]
	v_mfma_f32_16x16x32_bf16 v[40:43], v[132:135], v[190:193], v[40:43]
	v_mfma_f32_16x16x32_bf16 v[32:35], v[140:143], v[190:193], v[32:35]
	v_mfma_f32_16x16x32_bf16 v[24:27], v[132:135], v[200:203], v[24:27]
	v_mfma_f32_16x16x32_bf16 v[16:19], v[140:143], v[200:203], v[16:19]
	v_mfma_f32_16x16x32_bf16 v[8:11], v[132:135], v[212:215], v[8:11]
	v_mfma_f32_16x16x32_bf16 v[0:3], v[140:143], v[212:215], v[0:3]
	s_add_i32 s73, s73, 2
	s_add_u32 s44, s44, 0x100
	s_addc_u32 s45, s45, 0
	s_add_u32 s49, s49, 0x100
	s_addc_u32 s72, s72, 0
.LBB0_748:
	s_add_u32 s0, s44, 0xfffc0080
	s_addc_u32 s1, s45, -1
	s_add_i32 s74, 0, 0x10000
	s_cmp_eq_u32 s73, 12
	s_cselect_b32 s5, s6, s1
	s_cselect_b32 s4, s7, s0
	s_cselect_b32 s1, s39, s72
	s_cselect_b32 s0, s41, s49
	s_add_i32 s92, 0, 0x14000
	s_barrier
.Lrot_body_748:
	v_add_u32_e32 v124, s74, v199
	v_add_u32_e32 v140, s92, v199
	ds_read_b128 v[112:115], v124
	ds_read_b128 v[116:119], v124 offset:1024
	ds_read_b128 v[120:123], v124 offset:2048
	ds_read_b128 v[124:127], v124 offset:3072
	ds_read_b128 v[128:131], v140
	ds_read_b128 v[132:135], v140 offset:1024
	ds_read_b128 v[136:139], v140 offset:2048
	ds_read_b128 v[140:143], v140 offset:3072
	s_add_i32 m0, s63, 0xc000
	ds_read_b128 v[172:175], v207
	ds_read_b128 v[178:181], v207 offset:1024
	ds_read_b128 v[186:189], v207 offset:2048
	ds_read_b128 v[190:193], v207 offset:3072
	ds_read_b128 v[194:197], v207 offset:4096
	ds_read_b128 v[200:203], v207 offset:5120
	ds_read_b128 v[208:211], v207 offset:6144
	ds_read_b128 v[212:215], v207 offset:7168
	global_load_lds_dwordx4 v168, s[44:45]
	s_add_i32 m0, s63, 0xe000
	s_nop 0
	global_load_lds_dwordx4 v170, s[44:45]
	s_waitcnt vmcnt(8)
	s_waitcnt lgkmcnt(0)
	s_barrier
	s_waitcnt lgkmcnt(0)
	v_mfma_f32_16x16x32_bf16 v[156:159], v[112:115], v[172:175], v[156:159]
	v_mfma_f32_16x16x32_bf16 v[152:155], v[120:123], v[172:175], v[152:155]
	v_mfma_f32_16x16x32_bf16 v[108:111], v[112:115], v[186:189], v[108:111]
	v_mfma_f32_16x16x32_bf16 v[100:103], v[120:123], v[186:189], v[100:103]
	v_mfma_f32_16x16x32_bf16 v[92:95], v[112:115], v[194:197], v[92:95]
	v_mfma_f32_16x16x32_bf16 v[84:87], v[120:123], v[194:197], v[84:87]
	v_mfma_f32_16x16x32_bf16 v[76:79], v[112:115], v[208:211], v[76:79]
	v_mfma_f32_16x16x32_bf16 v[68:71], v[120:123], v[208:211], v[68:71]
	v_mfma_f32_16x16x32_bf16 v[156:159], v[116:119], v[178:181], v[156:159]
	v_mfma_f32_16x16x32_bf16 v[152:155], v[124:127], v[178:181], v[152:155]
	v_mfma_f32_16x16x32_bf16 v[108:111], v[116:119], v[190:193], v[108:111]
	v_mfma_f32_16x16x32_bf16 v[100:103], v[124:127], v[190:193], v[100:103]
	v_mfma_f32_16x16x32_bf16 v[92:95], v[116:119], v[200:203], v[92:95]
	v_mfma_f32_16x16x32_bf16 v[84:87], v[124:127], v[200:203], v[84:87]
	v_mfma_f32_16x16x32_bf16 v[76:79], v[116:119], v[212:215], v[76:79]
	v_mfma_f32_16x16x32_bf16 v[68:71], v[124:127], v[212:215], v[68:71]
	v_mfma_f32_16x16x32_bf16 v[148:151], v[128:131], v[172:175], v[148:151]
	v_mfma_f32_16x16x32_bf16 v[144:147], v[136:139], v[172:175], v[144:147]
	v_mfma_f32_16x16x32_bf16 v[104:107], v[128:131], v[186:189], v[104:107]
	v_mfma_f32_16x16x32_bf16 v[96:99], v[136:139], v[186:189], v[96:99]
	v_mfma_f32_16x16x32_bf16 v[88:91], v[128:131], v[194:197], v[88:91]
	v_mfma_f32_16x16x32_bf16 v[80:83], v[136:139], v[194:197], v[80:83]
	v_mfma_f32_16x16x32_bf16 v[72:75], v[128:131], v[208:211], v[72:75]
	v_mfma_f32_16x16x32_bf16 v[64:67], v[136:139], v[208:211], v[64:67]
	v_mfma_f32_16x16x32_bf16 v[148:151], v[132:135], v[178:181], v[148:151]
	v_mfma_f32_16x16x32_bf16 v[144:147], v[140:143], v[178:181], v[144:147]
	v_mfma_f32_16x16x32_bf16 v[104:107], v[132:135], v[190:193], v[104:107]
	v_mfma_f32_16x16x32_bf16 v[96:99], v[140:143], v[190:193], v[96:99]
	v_mfma_f32_16x16x32_bf16 v[88:91], v[132:135], v[200:203], v[88:91]
	v_mfma_f32_16x16x32_bf16 v[80:83], v[140:143], v[200:203], v[80:83]
	v_mfma_f32_16x16x32_bf16 v[72:75], v[132:135], v[212:215], v[72:75]
	v_mfma_f32_16x16x32_bf16 v[64:67], v[140:143], v[212:215], v[64:67]
	s_barrier
	s_add_i32 s74, s74, s62
	v_lshl_add_u64 v[182:183], s[0:1], 0, v[164:165]
	s_mov_b32 m0, s74
	ds_read_b128 v[172:175], v207 offset:16384
	ds_read_b128 v[178:181], v207 offset:17408
	ds_read_b128 v[186:189], v207 offset:18432
	ds_read_b128 v[190:193], v207 offset:19456
	ds_read_b128 v[194:197], v207 offset:20480
	ds_read_b128 v[200:203], v207 offset:21504
	ds_read_b128 v[208:211], v207 offset:22528
	ds_read_b128 v[212:215], v207 offset:23552
	global_load_lds_dwordx4 v164, s[0:1]
	s_add_i32 m0, s74, 0x2000
	s_add_u32 s74, s0, 0x40000
	v_lshl_add_u64 v[204:205], s[0:1], 0, v[160:161]
	s_addc_u32 s75, s1, 0
	s_add_i32 s92, s92, s62
	global_load_lds_dwordx4 v160, s[0:1]
	s_mov_b32 m0, s92
	v_lshl_add_u64 v[218:219], s[4:5], 0, v[162:163]
	global_load_lds_dwordx4 v164, s[74:75]
	s_add_i32 m0, s92, 0x2000
	s_nop 0
	global_load_lds_dwordx4 v160, s[74:75]
	v_lshl_add_u64 v[216:217], s[4:5], 0, v[166:167]
	s_mov_b32 m0, s63
	s_nop 0
	global_load_lds_dwordx4 v166, s[4:5]
	s_mov_b32 m0, s64
	s_nop 0
	global_load_lds_dwordx4 v162, s[4:5]
	s_waitcnt vmcnt(8)
	s_waitcnt lgkmcnt(0)
	s_barrier
	s_waitcnt lgkmcnt(0)
	v_mfma_f32_16x16x32_bf16 v[60:63], v[112:115], v[172:175], v[60:63]
	v_mfma_f32_16x16x32_bf16 v[56:59], v[120:123], v[172:175], v[56:59]
	v_mfma_f32_16x16x32_bf16 v[44:47], v[112:115], v[186:189], v[44:47]
	v_mfma_f32_16x16x32_bf16 v[36:39], v[120:123], v[186:189], v[36:39]
	v_mfma_f32_16x16x32_bf16 v[28:31], v[112:115], v[194:197], v[28:31]
	v_mfma_f32_16x16x32_bf16 v[20:23], v[120:123], v[194:197], v[20:23]
	v_mfma_f32_16x16x32_bf16 v[12:15], v[112:115], v[208:211], v[12:15]
	v_mfma_f32_16x16x32_bf16 v[4:7], v[120:123], v[208:211], v[4:7]
	v_mfma_f32_16x16x32_bf16 v[60:63], v[116:119], v[178:181], v[60:63]
	v_mfma_f32_16x16x32_bf16 v[56:59], v[124:127], v[178:181], v[56:59]
	v_mfma_f32_16x16x32_bf16 v[44:47], v[116:119], v[190:193], v[44:47]
	v_mfma_f32_16x16x32_bf16 v[36:39], v[124:127], v[190:193], v[36:39]
	v_mfma_f32_16x16x32_bf16 v[28:31], v[116:119], v[200:203], v[28:31]
	v_mfma_f32_16x16x32_bf16 v[20:23], v[124:127], v[200:203], v[20:23]
	v_mfma_f32_16x16x32_bf16 v[12:15], v[116:119], v[212:215], v[12:15]
	v_mfma_f32_16x16x32_bf16 v[4:7], v[124:127], v[212:215], v[4:7]
	v_mfma_f32_16x16x32_bf16 v[52:55], v[128:131], v[172:175], v[52:55]
	v_mfma_f32_16x16x32_bf16 v[48:51], v[136:139], v[172:175], v[48:51]
	v_mfma_f32_16x16x32_bf16 v[40:43], v[128:131], v[186:189], v[40:43]
	v_mfma_f32_16x16x32_bf16 v[32:35], v[136:139], v[186:189], v[32:35]
	v_mfma_f32_16x16x32_bf16 v[24:27], v[128:131], v[194:197], v[24:27]
	v_mfma_f32_16x16x32_bf16 v[16:19], v[136:139], v[194:197], v[16:19]
	v_mfma_f32_16x16x32_bf16 v[8:11], v[128:131], v[208:211], v[8:11]
	v_mfma_f32_16x16x32_bf16 v[0:3], v[136:139], v[208:211], v[0:3]
	v_mfma_f32_16x16x32_bf16 v[52:55], v[132:135], v[178:181], v[52:55]
	v_mfma_f32_16x16x32_bf16 v[48:51], v[140:143], v[178:181], v[48:51]
	v_mfma_f32_16x16x32_bf16 v[40:43], v[132:135], v[190:193], v[40:43]
	v_mfma_f32_16x16x32_bf16 v[32:35], v[140:143], v[190:193], v[32:35]
	v_mfma_f32_16x16x32_bf16 v[24:27], v[132:135], v[200:203], v[24:27]
	v_mfma_f32_16x16x32_bf16 v[16:19], v[140:143], v[200:203], v[16:19]
	v_mfma_f32_16x16x32_bf16 v[8:11], v[132:135], v[212:215], v[8:11]
	v_mfma_f32_16x16x32_bf16 v[0:3], v[140:143], v[212:215], v[0:3]
	s_barrier
	s_add_i32 s74, 0, 0x18000
	s_add_i32 s75, 0, 0x1c000
	v_add_u32_e32 v124, s74, v199
	v_add_u32_e32 v140, s75, v199
	ds_read_b128 v[112:115], v124
	ds_read_b128 v[116:119], v124 offset:1024
	ds_read_b128 v[120:123], v124 offset:2048
	ds_read_b128 v[124:127], v124 offset:3072
	ds_read_b128 v[128:131], v140
	ds_read_b128 v[132:135], v140 offset:1024
	ds_read_b128 v[136:139], v140 offset:2048
	ds_read_b128 v[140:143], v140 offset:3072
	s_add_u32 s4, s4, 0x40000
	s_addc_u32 s5, s5, 0
	s_mov_b32 m0, s65
	ds_read_b128 v[172:175], v207 offset:32768
	ds_read_b128 v[178:181], v207 offset:33792
	ds_read_b128 v[186:189], v207 offset:34816
	ds_read_b128 v[190:193], v207 offset:35840
	ds_read_b128 v[194:197], v207 offset:36864
	ds_read_b128 v[200:203], v207 offset:37888
	ds_read_b128 v[208:211], v207 offset:38912
	ds_read_b128 v[212:215], v207 offset:39936
	global_load_lds_dwordx4 v166, s[4:5]
	s_mov_b32 m0, s66
	s_nop 0
	global_load_lds_dwordx4 v162, s[4:5]
	s_waitcnt vmcnt(8)
	s_waitcnt lgkmcnt(0)
	s_barrier
	s_waitcnt lgkmcnt(0)
	v_mfma_f32_16x16x32_bf16 v[156:159], v[112:115], v[172:175], v[156:159]
	v_mfma_f32_16x16x32_bf16 v[152:155], v[120:123], v[172:175], v[152:155]
	v_mfma_f32_16x16x32_bf16 v[108:111], v[112:115], v[186:189], v[108:111]
	v_mfma_f32_16x16x32_bf16 v[100:103], v[120:123], v[186:189], v[100:103]
	v_mfma_f32_16x16x32_bf16 v[92:95], v[112:115], v[194:197], v[92:95]
	v_mfma_f32_16x16x32_bf16 v[84:87], v[120:123], v[194:197], v[84:87]
	v_mfma_f32_16x16x32_bf16 v[76:79], v[112:115], v[208:211], v[76:79]
	v_mfma_f32_16x16x32_bf16 v[68:71], v[120:123], v[208:211], v[68:71]
	v_mfma_f32_16x16x32_bf16 v[156:159], v[116:119], v[178:181], v[156:159]
	v_mfma_f32_16x16x32_bf16 v[152:155], v[124:127], v[178:181], v[152:155]
	v_mfma_f32_16x16x32_bf16 v[108:111], v[116:119], v[190:193], v[108:111]
	v_mfma_f32_16x16x32_bf16 v[100:103], v[124:127], v[190:193], v[100:103]
	v_mfma_f32_16x16x32_bf16 v[92:95], v[116:119], v[200:203], v[92:95]
	v_mfma_f32_16x16x32_bf16 v[84:87], v[124:127], v[200:203], v[84:87]
	v_mfma_f32_16x16x32_bf16 v[76:79], v[116:119], v[212:215], v[76:79]
	v_mfma_f32_16x16x32_bf16 v[68:71], v[124:127], v[212:215], v[68:71]
	v_mfma_f32_16x16x32_bf16 v[148:151], v[128:131], v[172:175], v[148:151]
	v_mfma_f32_16x16x32_bf16 v[144:147], v[136:139], v[172:175], v[144:147]
	v_mfma_f32_16x16x32_bf16 v[104:107], v[128:131], v[186:189], v[104:107]
	v_mfma_f32_16x16x32_bf16 v[96:99], v[136:139], v[186:189], v[96:99]
	v_mfma_f32_16x16x32_bf16 v[88:91], v[128:131], v[194:197], v[88:91]
	v_mfma_f32_16x16x32_bf16 v[80:83], v[136:139], v[194:197], v[80:83]
	v_mfma_f32_16x16x32_bf16 v[72:75], v[128:131], v[208:211], v[72:75]
	v_mfma_f32_16x16x32_bf16 v[64:67], v[136:139], v[208:211], v[64:67]
	v_mfma_f32_16x16x32_bf16 v[148:151], v[132:135], v[178:181], v[148:151]
	v_mfma_f32_16x16x32_bf16 v[144:147], v[140:143], v[178:181], v[144:147]
	v_mfma_f32_16x16x32_bf16 v[104:107], v[132:135], v[190:193], v[104:107]
	v_mfma_f32_16x16x32_bf16 v[96:99], v[140:143], v[190:193], v[96:99]
	v_mfma_f32_16x16x32_bf16 v[88:91], v[132:135], v[200:203], v[88:91]
	v_mfma_f32_16x16x32_bf16 v[80:83], v[140:143], v[200:203], v[80:83]
	v_mfma_f32_16x16x32_bf16 v[72:75], v[132:135], v[212:215], v[72:75]
	v_mfma_f32_16x16x32_bf16 v[64:67], v[140:143], v[212:215], v[64:67]
	s_barrier
	s_add_i32 s4, s74, s62
	v_lshl_add_u64 v[182:183], v[182:183], 0, s[82:83]
	s_mov_b32 m0, s4
	ds_read_b128 v[172:175], v207 offset:49152
	ds_read_b128 v[178:181], v207 offset:50176
	ds_read_b128 v[186:189], v207 offset:51200
	ds_read_b128 v[190:193], v207 offset:52224
	ds_read_b128 v[194:197], v207 offset:53248
	ds_read_b128 v[200:203], v207 offset:54272
	ds_read_b128 v[208:211], v207 offset:55296
	ds_read_b128 v[212:215], v207 offset:56320
	global_load_lds_dwordx4 v[182:183], off
	s_add_i32 m0, s4, 0x2000
	s_add_u32 s0, s0, 0x40080
	v_lshl_add_u64 v[182:183], v[204:205], 0, s[82:83]
	s_addc_u32 s1, s1, 0
	s_add_i32 s4, s75, s62
	global_load_lds_dwordx4 v[182:183], off
	s_mov_b32 m0, s4
	s_nop 0
	global_load_lds_dwordx4 v164, s[0:1]
	s_add_i32 m0, s4, 0x2000
	s_nop 0
	global_load_lds_dwordx4 v160, s[0:1]
	v_lshl_add_u64 v[182:183], v[216:217], 0, s[82:83]
	s_mov_b32 m0, s69
	s_nop 0
	global_load_lds_dwordx4 v[182:183], off
	v_lshl_add_u64 v[182:183], v[218:219], 0, s[82:83]
	s_mov_b32 m0, s70
	s_nop 0
	global_load_lds_dwordx4 v[182:183], off
	s_waitcnt vmcnt(8)
	s_waitcnt lgkmcnt(0)
	s_barrier
	s_waitcnt lgkmcnt(0)
	v_mfma_f32_16x16x32_bf16 v[60:63], v[112:115], v[172:175], v[60:63]
	v_mfma_f32_16x16x32_bf16 v[56:59], v[120:123], v[172:175], v[56:59]
	v_mfma_f32_16x16x32_bf16 v[44:47], v[112:115], v[186:189], v[44:47]
	v_mfma_f32_16x16x32_bf16 v[36:39], v[120:123], v[186:189], v[36:39]
	v_mfma_f32_16x16x32_bf16 v[28:31], v[112:115], v[194:197], v[28:31]
	v_mfma_f32_16x16x32_bf16 v[20:23], v[120:123], v[194:197], v[20:23]
	v_mfma_f32_16x16x32_bf16 v[12:15], v[112:115], v[208:211], v[12:15]
	v_mfma_f32_16x16x32_bf16 v[4:7], v[120:123], v[208:211], v[4:7]
	v_mfma_f32_16x16x32_bf16 v[60:63], v[116:119], v[178:181], v[60:63]
	v_mfma_f32_16x16x32_bf16 v[56:59], v[124:127], v[178:181], v[56:59]
	v_mfma_f32_16x16x32_bf16 v[44:47], v[116:119], v[190:193], v[44:47]
	v_mfma_f32_16x16x32_bf16 v[36:39], v[124:127], v[190:193], v[36:39]
	v_mfma_f32_16x16x32_bf16 v[28:31], v[116:119], v[200:203], v[28:31]
	v_mfma_f32_16x16x32_bf16 v[20:23], v[124:127], v[200:203], v[20:23]
	v_mfma_f32_16x16x32_bf16 v[12:15], v[116:119], v[212:215], v[12:15]
	v_mfma_f32_16x16x32_bf16 v[4:7], v[124:127], v[212:215], v[4:7]
	v_mfma_f32_16x16x32_bf16 v[52:55], v[128:131], v[172:175], v[52:55]
	v_mfma_f32_16x16x32_bf16 v[48:51], v[136:139], v[172:175], v[48:51]
	v_mfma_f32_16x16x32_bf16 v[40:43], v[128:131], v[186:189], v[40:43]
	v_mfma_f32_16x16x32_bf16 v[32:35], v[136:139], v[186:189], v[32:35]
	v_mfma_f32_16x16x32_bf16 v[24:27], v[128:131], v[194:197], v[24:27]
	v_mfma_f32_16x16x32_bf16 v[16:19], v[136:139], v[194:197], v[16:19]
	v_mfma_f32_16x16x32_bf16 v[8:11], v[128:131], v[208:211], v[8:11]
	v_mfma_f32_16x16x32_bf16 v[0:3], v[136:139], v[208:211], v[0:3]
	v_mfma_f32_16x16x32_bf16 v[52:55], v[132:135], v[178:181], v[52:55]
	v_mfma_f32_16x16x32_bf16 v[48:51], v[140:143], v[178:181], v[48:51]
	v_mfma_f32_16x16x32_bf16 v[40:43], v[132:135], v[190:193], v[40:43]
	v_mfma_f32_16x16x32_bf16 v[32:35], v[140:143], v[190:193], v[32:35]
	v_mfma_f32_16x16x32_bf16 v[24:27], v[132:135], v[200:203], v[24:27]
	v_mfma_f32_16x16x32_bf16 v[16:19], v[140:143], v[200:203], v[16:19]
	v_mfma_f32_16x16x32_bf16 v[8:11], v[132:135], v[212:215], v[8:11]
	v_mfma_f32_16x16x32_bf16 v[0:3], v[140:143], v[212:215], v[0:3]
	s_add_i32 s73, s73, 2
	s_add_u32 s44, s44, 0x100
	s_addc_u32 s45, s45, 0
	s_add_u32 s49, s49, 0x100
	s_addc_u32 s72, s72, 0
	s_cmp_gt_u32 s73, 13
	s_cbranch_scc0 .LBB0_748
	s_barrier
	s_and_b64 vcc, exec, s[90:91]
	s_cbranch_vccz .LBB0_751
	s_barrier

.LBB0_929:
	s_add_u32 s69, s0, 0x100
	v_mov_b32_e32 v0, 0
	s_addc_u32 s70, s1, 0
	s_mov_b32 s71, -2
	v_mov_b32_e32 v1, v0
	v_mov_b32_e32 v2, v0
	v_mov_b32_e32 v3, v0
	v_mov_b32_e32 v4, v0
	v_mov_b32_e32 v5, v0
	v_mov_b32_e32 v6, v0
	v_mov_b32_e32 v7, v0
	v_mov_b32_e32 v16, v0
	v_mov_b32_e32 v17, v0
	v_mov_b32_e32 v18, v0
	v_mov_b32_e32 v19, v0
	v_mov_b32_e32 v20, v0
	v_mov_b32_e32 v21, v0
	v_mov_b32_e32 v22, v0
	v_mov_b32_e32 v23, v0
	s_waitcnt vmcnt(0)
	v_mov_b32_e32 v32, v0
	v_mov_b32_e32 v33, v0
	v_mov_b32_e32 v34, v0
	v_mov_b32_e32 v35, v0
	v_mov_b32_e32 v36, v0
	v_mov_b32_e32 v37, v0
	v_mov_b32_e32 v38, v0
	v_mov_b32_e32 v39, v0
	v_mov_b32_e32 v48, v0
	v_mov_b32_e32 v49, v0
	v_mov_b32_e32 v50, v0
	v_mov_b32_e32 v51, v0
	v_mov_b32_e32 v52, v0
	v_mov_b32_e32 v53, v0
	v_mov_b32_e32 v54, v0
	v_mov_b32_e32 v55, v0
	v_mov_b32_e32 v8, v0
	v_mov_b32_e32 v9, v0
	v_mov_b32_e32 v10, v0
	v_mov_b32_e32 v11, v0
	v_mov_b32_e32 v12, v0
	v_mov_b32_e32 v13, v0
	v_mov_b32_e32 v14, v0
	v_mov_b32_e32 v15, v0
	v_mov_b32_e32 v24, v0
	v_mov_b32_e32 v25, v0
	v_mov_b32_e32 v26, v0
	v_mov_b32_e32 v27, v0
	v_mov_b32_e32 v28, v0
	v_mov_b32_e32 v29, v0
	v_mov_b32_e32 v30, v0
	v_mov_b32_e32 v31, v0
	v_mov_b32_e32 v40, v0
	v_mov_b32_e32 v41, v0
	v_mov_b32_e32 v42, v0
	v_mov_b32_e32 v43, v0
	v_mov_b32_e32 v44, v0
	v_mov_b32_e32 v45, v0
	v_mov_b32_e32 v46, v0
	v_mov_b32_e32 v47, v0
	v_mov_b32_e32 v56, v0
	v_mov_b32_e32 v57, v0
	v_mov_b32_e32 v58, v0
	v_mov_b32_e32 v59, v0
	v_mov_b32_e32 v60, v0
	v_mov_b32_e32 v61, v0
	v_mov_b32_e32 v62, v0
	v_mov_b32_e32 v63, v0
	v_mov_b32_e32 v64, v0
	v_mov_b32_e32 v65, v0
	v_mov_b32_e32 v66, v0
	v_mov_b32_e32 v67, v0
	v_mov_b32_e32 v68, v0
	v_mov_b32_e32 v69, v0
	v_mov_b32_e32 v70, v0
	v_mov_b32_e32 v71, v0
	v_mov_b32_e32 v80, v0
	v_mov_b32_e32 v81, v0
	v_mov_b32_e32 v82, v0
	v_mov_b32_e32 v83, v0
	v_mov_b32_e32 v84, v0
	v_mov_b32_e32 v85, v0
	v_mov_b32_e32 v86, v0
	v_mov_b32_e32 v87, v0
	v_mov_b32_e32 v96, v0
	v_mov_b32_e32 v97, v0
	v_mov_b32_e32 v98, v0
	v_mov_b32_e32 v99, v0
	v_mov_b32_e32 v100, v0
	v_mov_b32_e32 v101, v0
	v_mov_b32_e32 v102, v0
	v_mov_b32_e32 v103, v0
	v_mov_b32_e32 v112, v0
	v_mov_b32_e32 v113, v0
	v_mov_b32_e32 v114, v0
	v_mov_b32_e32 v115, v0
	v_mov_b32_e32 v116, v0
	v_mov_b32_e32 v117, v0
	v_mov_b32_e32 v118, v0
	v_mov_b32_e32 v119, v0
	v_mov_b32_e32 v72, v0
	v_mov_b32_e32 v73, v0
	v_mov_b32_e32 v74, v0
	v_mov_b32_e32 v75, v0
	v_mov_b32_e32 v76, v0
	v_mov_b32_e32 v77, v0
	v_mov_b32_e32 v78, v0
	v_mov_b32_e32 v79, v0
	v_mov_b32_e32 v88, v0
	v_mov_b32_e32 v89, v0
	v_mov_b32_e32 v90, v0
	v_mov_b32_e32 v91, v0
	v_mov_b32_e32 v92, v0
	v_mov_b32_e32 v93, v0
	v_mov_b32_e32 v94, v0
	v_mov_b32_e32 v95, v0
	v_mov_b32_e32 v104, v0
	v_mov_b32_e32 v105, v0
	v_mov_b32_e32 v106, v0
	v_mov_b32_e32 v107, v0
	v_mov_b32_e32 v108, v0
	v_mov_b32_e32 v109, v0
	v_mov_b32_e32 v110, v0
	v_mov_b32_e32 v111, v0
	v_mov_b32_e32 v120, v0
	v_mov_b32_e32 v121, v0
	v_mov_b32_e32 v122, v0
	v_mov_b32_e32 v123, v0
	v_mov_b32_e32 v124, v0
	v_mov_b32_e32 v125, v0
	v_mov_b32_e32 v126, v0
	v_mov_b32_e32 v127, v0
	s_add_u32 s0, s54, 0x100
	s_addc_u32 s1, s55, 0
	s_add_i32 s72, 0, 0x10000
	s_cmp_eq_u32 s71, 40
	s_cselect_b32 s43, s51, s1
	s_cselect_b32 s42, s50, s0
	s_cselect_b32 s5, s53, s70
	s_cselect_b32 s4, s52, s69
	s_add_i32 s73, 0, 0x14000
	s_branch .Lrot_body_930
.LBB0_930:
	s_add_u32 s0, s54, 0x100
	s_addc_u32 s1, s55, 0
	s_add_i32 s72, 0, 0x10000
	s_cmp_eq_u32 s71, 40
	s_cselect_b32 s43, s51, s1
	s_cselect_b32 s42, s50, s0
	s_cselect_b32 s5, s53, s70
	s_cselect_b32 s4, s52, s69
	s_add_i32 s73, 0, 0x14000
	s_barrier
.Lrot_body_930:
	v_add_u32_e32 v140, s72, v164
	v_add_u32_e32 v162, s73, v164
	ds_read_b128 v[128:131], v140
	ds_read_b128 v[132:135], v140 offset:1024
	ds_read_b128 v[136:139], v140 offset:2048
	ds_read_b128 v[140:143], v140 offset:3072
	ds_read_b128 v[154:157], v162
	ds_read_b128 v[158:161], v162 offset:1024
	ds_read_b128 v[166:169], v162 offset:2048
	ds_read_b128 v[170:173], v162 offset:3072
	s_add_i32 m0, s20, 0xc000
	ds_read_b128 v[178:181], v165
	ds_read_b128 v[186:189], v165 offset:1024
	ds_read_b128 v[190:193], v165 offset:2048
	ds_read_b128 v[194:197], v165 offset:3072
	ds_read_b128 v[198:201], v165 offset:4096
	ds_read_b128 v[202:205], v165 offset:5120
	ds_read_b128 v[206:209], v165 offset:6144
	ds_read_b128 v[210:213], v165 offset:7168
	global_load_lds_dwordx4 v150, s[54:55]
	s_add_i32 m0, s20, 0xe000
	s_nop 0
	global_load_lds_dwordx4 v152, s[54:55]
	s_waitcnt vmcnt(8)
	s_waitcnt lgkmcnt(0)
	s_barrier
	s_waitcnt lgkmcnt(0)
	v_mfma_f32_16x16x32_bf16 v[124:127], v[128:131], v[178:181], v[124:127]
	v_mfma_f32_16x16x32_bf16 v[120:123], v[136:139], v[178:181], v[120:123]
	v_mfma_f32_16x16x32_bf16 v[108:111], v[128:131], v[190:193], v[108:111]
	v_mfma_f32_16x16x32_bf16 v[104:107], v[136:139], v[190:193], v[104:107]
	v_mfma_f32_16x16x32_bf16 v[92:95], v[128:131], v[198:201], v[92:95]
	v_mfma_f32_16x16x32_bf16 v[88:91], v[136:139], v[198:201], v[88:91]
	v_mfma_f32_16x16x32_bf16 v[76:79], v[128:131], v[206:209], v[76:79]
	v_mfma_f32_16x16x32_bf16 v[72:75], v[136:139], v[206:209], v[72:75]
	v_mfma_f32_16x16x32_bf16 v[124:127], v[132:135], v[186:189], v[124:127]
	v_mfma_f32_16x16x32_bf16 v[120:123], v[140:143], v[186:189], v[120:123]
	v_mfma_f32_16x16x32_bf16 v[108:111], v[132:135], v[194:197], v[108:111]
	v_mfma_f32_16x16x32_bf16 v[104:107], v[140:143], v[194:197], v[104:107]
	v_mfma_f32_16x16x32_bf16 v[92:95], v[132:135], v[202:205], v[92:95]
	v_mfma_f32_16x16x32_bf16 v[88:91], v[140:143], v[202:205], v[88:91]
	v_mfma_f32_16x16x32_bf16 v[76:79], v[132:135], v[210:213], v[76:79]
	v_mfma_f32_16x16x32_bf16 v[72:75], v[140:143], v[210:213], v[72:75]
	v_mfma_f32_16x16x32_bf16 v[116:119], v[154:157], v[178:181], v[116:119]
	v_mfma_f32_16x16x32_bf16 v[112:115], v[166:169], v[178:181], v[112:115]
	v_mfma_f32_16x16x32_bf16 v[100:103], v[154:157], v[190:193], v[100:103]
	v_mfma_f32_16x16x32_bf16 v[96:99], v[166:169], v[190:193], v[96:99]
	v_mfma_f32_16x16x32_bf16 v[84:87], v[154:157], v[198:201], v[84:87]
	v_mfma_f32_16x16x32_bf16 v[80:83], v[166:169], v[198:201], v[80:83]
	v_mfma_f32_16x16x32_bf16 v[68:71], v[154:157], v[206:209], v[68:71]
	v_mfma_f32_16x16x32_bf16 v[64:67], v[166:169], v[206:209], v[64:67]
	v_mfma_f32_16x16x32_bf16 v[116:119], v[158:161], v[186:189], v[116:119]
	v_mfma_f32_16x16x32_bf16 v[112:115], v[170:173], v[186:189], v[112:115]
	v_mfma_f32_16x16x32_bf16 v[100:103], v[158:161], v[194:197], v[100:103]
	v_mfma_f32_16x16x32_bf16 v[96:99], v[170:173], v[194:197], v[96:99]
	v_mfma_f32_16x16x32_bf16 v[84:87], v[158:161], v[202:205], v[84:87]
	v_mfma_f32_16x16x32_bf16 v[80:83], v[170:173], v[202:205], v[80:83]
	v_mfma_f32_16x16x32_bf16 v[68:71], v[158:161], v[210:213], v[68:71]
	v_mfma_f32_16x16x32_bf16 v[64:67], v[170:173], v[210:213], v[64:67]
	s_barrier
	s_add_i32 s54, s72, s12
	v_lshl_add_u64 v[162:163], s[4:5], 0, v[176:177]
	s_mov_b32 m0, s54
	ds_read_b128 v[178:181], v165 offset:16384
	ds_read_b128 v[186:189], v165 offset:17408
	ds_read_b128 v[190:193], v165 offset:18432
	ds_read_b128 v[194:197], v165 offset:19456
	ds_read_b128 v[198:201], v165 offset:20480
	ds_read_b128 v[202:205], v165 offset:21504
	ds_read_b128 v[206:209], v165 offset:22528
	ds_read_b128 v[210:213], v165 offset:23552
	global_load_lds_dwordx4 v176, s[4:5]
	s_add_i32 m0, s54, 0x2000
	s_add_u32 s54, s4, 0xb0000
	v_lshl_add_u64 v[174:175], s[4:5], 0, v[144:145]
	s_addc_u32 s55, s5, 0
	s_add_i32 s72, s73, s12
	global_load_lds_dwordx4 v144, s[4:5]
	s_mov_b32 m0, s72
	v_lshl_add_u64 v[214:215], s[42:43], 0, v[146:147]
	global_load_lds_dwordx4 v176, s[54:55]
	s_add_i32 m0, s72, 0x2000
	s_nop 0
	global_load_lds_dwordx4 v144, s[54:55]
	v_lshl_add_u64 v[182:183], s[42:43], 0, v[148:149]
	s_mov_b32 m0, s20
	s_nop 0
	global_load_lds_dwordx4 v148, s[42:43]
	s_mov_b32 m0, s27
	s_nop 0
	global_load_lds_dwordx4 v146, s[42:43]
	s_waitcnt vmcnt(8)
	s_waitcnt lgkmcnt(0)
	s_barrier
	s_waitcnt lgkmcnt(0)
	v_mfma_f32_16x16x32_bf16 v[60:63], v[128:131], v[178:181], v[60:63]
	v_mfma_f32_16x16x32_bf16 v[56:59], v[136:139], v[178:181], v[56:59]
	v_mfma_f32_16x16x32_bf16 v[44:47], v[128:131], v[190:193], v[44:47]
	v_mfma_f32_16x16x32_bf16 v[40:43], v[136:139], v[190:193], v[40:43]
	v_mfma_f32_16x16x32_bf16 v[28:31], v[128:131], v[198:201], v[28:31]
	v_mfma_f32_16x16x32_bf16 v[24:27], v[136:139], v[198:201], v[24:27]
	v_mfma_f32_16x16x32_bf16 v[12:15], v[128:131], v[206:209], v[12:15]
	v_mfma_f32_16x16x32_bf16 v[8:11], v[136:139], v[206:209], v[8:11]
	v_mfma_f32_16x16x32_bf16 v[60:63], v[132:135], v[186:189], v[60:63]
	v_mfma_f32_16x16x32_bf16 v[56:59], v[140:143], v[186:189], v[56:59]
	v_mfma_f32_16x16x32_bf16 v[44:47], v[132:135], v[194:197], v[44:47]
	v_mfma_f32_16x16x32_bf16 v[40:43], v[140:143], v[194:197], v[40:43]
	v_mfma_f32_16x16x32_bf16 v[28:31], v[132:135], v[202:205], v[28:31]
	v_mfma_f32_16x16x32_bf16 v[24:27], v[140:143], v[202:205], v[24:27]
	v_mfma_f32_16x16x32_bf16 v[12:15], v[132:135], v[210:213], v[12:15]
	v_mfma_f32_16x16x32_bf16 v[8:11], v[140:143], v[210:213], v[8:11]
	v_mfma_f32_16x16x32_bf16 v[52:55], v[154:157], v[178:181], v[52:55]
	v_mfma_f32_16x16x32_bf16 v[48:51], v[166:169], v[178:181], v[48:51]
	v_mfma_f32_16x16x32_bf16 v[36:39], v[154:157], v[190:193], v[36:39]
	v_mfma_f32_16x16x32_bf16 v[32:35], v[166:169], v[190:193], v[32:35]
	v_mfma_f32_16x16x32_bf16 v[20:23], v[154:157], v[198:201], v[20:23]
	v_mfma_f32_16x16x32_bf16 v[16:19], v[166:169], v[198:201], v[16:19]
	v_mfma_f32_16x16x32_bf16 v[4:7], v[154:157], v[206:209], v[4:7]
	v_mfma_f32_16x16x32_bf16 v[0:3], v[166:169], v[206:209], v[0:3]
	v_mfma_f32_16x16x32_bf16 v[52:55], v[158:161], v[186:189], v[52:55]
	v_mfma_f32_16x16x32_bf16 v[48:51], v[170:173], v[186:189], v[48:51]
	v_mfma_f32_16x16x32_bf16 v[36:39], v[158:161], v[194:197], v[36:39]
	v_mfma_f32_16x16x32_bf16 v[32:35], v[170:173], v[194:197], v[32:35]
	v_mfma_f32_16x16x32_bf16 v[20:23], v[158:161], v[202:205], v[20:23]
	v_mfma_f32_16x16x32_bf16 v[16:19], v[170:173], v[202:205], v[16:19]
	v_mfma_f32_16x16x32_bf16 v[4:7], v[158:161], v[210:213], v[4:7]
	v_mfma_f32_16x16x32_bf16 v[0:3], v[170:173], v[210:213], v[0:3]
	s_barrier
	s_add_i32 s54, 0, 0x18000
	s_add_i32 s55, 0, 0x1c000
	v_add_u32_e32 v140, s54, v164
	v_add_u32_e32 v170, s55, v164
	ds_read_b128 v[128:131], v140
	ds_read_b128 v[132:135], v140 offset:1024
	ds_read_b128 v[136:139], v140 offset:2048
	ds_read_b128 v[140:143], v140 offset:3072
	ds_read_b128 v[154:157], v170
	ds_read_b128 v[158:161], v170 offset:1024
	ds_read_b128 v[166:169], v170 offset:2048
	ds_read_b128 v[170:173], v170 offset:3072
	s_add_u32 s42, s42, 0xb0000
	s_addc_u32 s43, s43, 0
	s_mov_b32 m0, s47
	ds_read_b128 v[178:181], v165 offset:32768
	ds_read_b128 v[186:189], v165 offset:33792
	ds_read_b128 v[190:193], v165 offset:34816
	ds_read_b128 v[194:197], v165 offset:35840
	ds_read_b128 v[198:201], v165 offset:36864
	ds_read_b128 v[202:205], v165 offset:37888
	ds_read_b128 v[206:209], v165 offset:38912
	ds_read_b128 v[210:213], v165 offset:39936
	global_load_lds_dwordx4 v148, s[42:43]
	s_mov_b32 m0, s56
	s_nop 0
	global_load_lds_dwordx4 v146, s[42:43]
	s_waitcnt vmcnt(8)
	s_waitcnt lgkmcnt(0)
	s_barrier
	s_waitcnt lgkmcnt(0)
	v_mfma_f32_16x16x32_bf16 v[124:127], v[128:131], v[178:181], v[124:127]
	v_mfma_f32_16x16x32_bf16 v[120:123], v[136:139], v[178:181], v[120:123]
	v_mfma_f32_16x16x32_bf16 v[108:111], v[128:131], v[190:193], v[108:111]
	v_mfma_f32_16x16x32_bf16 v[104:107], v[136:139], v[190:193], v[104:107]
	v_mfma_f32_16x16x32_bf16 v[92:95], v[128:131], v[198:201], v[92:95]
	v_mfma_f32_16x16x32_bf16 v[88:91], v[136:139], v[198:201], v[88:91]
	v_mfma_f32_16x16x32_bf16 v[76:79], v[128:131], v[206:209], v[76:79]
	v_mfma_f32_16x16x32_bf16 v[72:75], v[136:139], v[206:209], v[72:75]
	v_mfma_f32_16x16x32_bf16 v[124:127], v[132:135], v[186:189], v[124:127]
	v_mfma_f32_16x16x32_bf16 v[120:123], v[140:143], v[186:189], v[120:123]
	v_mfma_f32_16x16x32_bf16 v[108:111], v[132:135], v[194:197], v[108:111]
	v_mfma_f32_16x16x32_bf16 v[104:107], v[140:143], v[194:197], v[104:107]
	v_mfma_f32_16x16x32_bf16 v[92:95], v[132:135], v[202:205], v[92:95]
	v_mfma_f32_16x16x32_bf16 v[88:91], v[140:143], v[202:205], v[88:91]
	v_mfma_f32_16x16x32_bf16 v[76:79], v[132:135], v[210:213], v[76:79]
	v_mfma_f32_16x16x32_bf16 v[72:75], v[140:143], v[210:213], v[72:75]
	v_mfma_f32_16x16x32_bf16 v[116:119], v[154:157], v[178:181], v[116:119]
	v_mfma_f32_16x16x32_bf16 v[112:115], v[166:169], v[178:181], v[112:115]
	v_mfma_f32_16x16x32_bf16 v[100:103], v[154:157], v[190:193], v[100:103]
	v_mfma_f32_16x16x32_bf16 v[96:99], v[166:169], v[190:193], v[96:99]
	v_mfma_f32_16x16x32_bf16 v[84:87], v[154:157], v[198:201], v[84:87]
	v_mfma_f32_16x16x32_bf16 v[80:83], v[166:169], v[198:201], v[80:83]
	v_mfma_f32_16x16x32_bf16 v[68:71], v[154:157], v[206:209], v[68:71]
	v_mfma_f32_16x16x32_bf16 v[64:67], v[166:169], v[206:209], v[64:67]
	v_mfma_f32_16x16x32_bf16 v[116:119], v[158:161], v[186:189], v[116:119]
	v_mfma_f32_16x16x32_bf16 v[112:115], v[170:173], v[186:189], v[112:115]
	v_mfma_f32_16x16x32_bf16 v[100:103], v[158:161], v[194:197], v[100:103]
	v_mfma_f32_16x16x32_bf16 v[96:99], v[170:173], v[194:197], v[96:99]
	v_mfma_f32_16x16x32_bf16 v[84:87], v[158:161], v[202:205], v[84:87]
	v_mfma_f32_16x16x32_bf16 v[80:83], v[170:173], v[202:205], v[80:83]
	v_mfma_f32_16x16x32_bf16 v[68:71], v[158:161], v[210:213], v[68:71]
	v_mfma_f32_16x16x32_bf16 v[64:67], v[170:173], v[210:213], v[64:67]
	s_barrier
	s_add_i32 s42, s54, s12
	v_lshl_add_u64 v[162:163], v[162:163], 0, s[82:83]
	s_mov_b32 m0, s42
	ds_read_b128 v[178:181], v165 offset:49152
	ds_read_b128 v[186:189], v165 offset:50176
	ds_read_b128 v[190:193], v165 offset:51200
	ds_read_b128 v[194:197], v165 offset:52224
	ds_read_b128 v[198:201], v165 offset:53248
	ds_read_b128 v[202:205], v165 offset:54272
	ds_read_b128 v[206:209], v165 offset:55296
	ds_read_b128 v[210:213], v165 offset:56320
	global_load_lds_dwordx4 v[162:163], off
	s_add_i32 m0, s42, 0x2000
	s_add_u32 s4, s4, 0xb0080
	v_lshl_add_u64 v[162:163], v[174:175], 0, s[82:83]
	s_addc_u32 s5, s5, 0
	s_add_i32 s42, s55, s12
	global_load_lds_dwordx4 v[162:163], off
	s_mov_b32 m0, s42
	s_nop 0
	global_load_lds_dwordx4 v176, s[4:5]
	s_add_i32 m0, s42, 0x2000
	s_nop 0
	global_load_lds_dwordx4 v144, s[4:5]
	v_lshl_add_u64 v[162:163], v[182:183], 0, s[82:83]
	s_mov_b32 m0, s62
	s_nop 0
	global_load_lds_dwordx4 v[162:163], off
	v_lshl_add_u64 v[162:163], v[214:215], 0, s[82:83]
	s_mov_b32 m0, s63
	s_nop 0
	global_load_lds_dwordx4 v[162:163], off
	s_waitcnt vmcnt(8)
	s_waitcnt lgkmcnt(0)
	s_barrier
	s_waitcnt lgkmcnt(0)
	v_mfma_f32_16x16x32_bf16 v[60:63], v[128:131], v[178:181], v[60:63]
	v_mfma_f32_16x16x32_bf16 v[56:59], v[136:139], v[178:181], v[56:59]
	v_mfma_f32_16x16x32_bf16 v[44:47], v[128:131], v[190:193], v[44:47]
	v_mfma_f32_16x16x32_bf16 v[40:43], v[136:139], v[190:193], v[40:43]
	v_mfma_f32_16x16x32_bf16 v[28:31], v[128:131], v[198:201], v[28:31]
	v_mfma_f32_16x16x32_bf16 v[24:27], v[136:139], v[198:201], v[24:27]
	v_mfma_f32_16x16x32_bf16 v[12:15], v[128:131], v[206:209], v[12:15]
	v_mfma_f32_16x16x32_bf16 v[8:11], v[136:139], v[206:209], v[8:11]
	v_mfma_f32_16x16x32_bf16 v[60:63], v[132:135], v[186:189], v[60:63]
	v_mfma_f32_16x16x32_bf16 v[56:59], v[140:143], v[186:189], v[56:59]
	v_mfma_f32_16x16x32_bf16 v[44:47], v[132:135], v[194:197], v[44:47]
	v_mfma_f32_16x16x32_bf16 v[40:43], v[140:143], v[194:197], v[40:43]
	v_mfma_f32_16x16x32_bf16 v[28:31], v[132:135], v[202:205], v[28:31]
	v_mfma_f32_16x16x32_bf16 v[24:27], v[140:143], v[202:205], v[24:27]
	v_mfma_f32_16x16x32_bf16 v[12:15], v[132:135], v[210:213], v[12:15]
	v_mfma_f32_16x16x32_bf16 v[8:11], v[140:143], v[210:213], v[8:11]
	v_mfma_f32_16x16x32_bf16 v[52:55], v[154:157], v[178:181], v[52:55]
	v_mfma_f32_16x16x32_bf16 v[48:51], v[166:169], v[178:181], v[48:51]
	v_mfma_f32_16x16x32_bf16 v[36:39], v[154:157], v[190:193], v[36:39]
	v_mfma_f32_16x16x32_bf16 v[32:35], v[166:169], v[190:193], v[32:35]
	v_mfma_f32_16x16x32_bf16 v[20:23], v[154:157], v[198:201], v[20:23]
	v_mfma_f32_16x16x32_bf16 v[16:19], v[166:169], v[198:201], v[16:19]
	v_mfma_f32_16x16x32_bf16 v[4:7], v[154:157], v[206:209], v[4:7]
	v_mfma_f32_16x16x32_bf16 v[0:3], v[166:169], v[206:209], v[0:3]
	v_mfma_f32_16x16x32_bf16 v[52:55], v[158:161], v[186:189], v[52:55]
	v_mfma_f32_16x16x32_bf16 v[48:51], v[170:173], v[186:189], v[48:51]
	v_mfma_f32_16x16x32_bf16 v[36:39], v[158:161], v[194:197], v[36:39]
	v_mfma_f32_16x16x32_bf16 v[32:35], v[170:173], v[194:197], v[32:35]
	v_mfma_f32_16x16x32_bf16 v[20:23], v[158:161], v[202:205], v[20:23]
	v_mfma_f32_16x16x32_bf16 v[16:19], v[170:173], v[202:205], v[16:19]
	v_mfma_f32_16x16x32_bf16 v[4:7], v[158:161], v[210:213], v[4:7]
	v_mfma_f32_16x16x32_bf16 v[0:3], v[170:173], v[210:213], v[0:3]
	s_add_i32 s71, s71, 2
	s_add_u32 s69, s69, 0x100
	s_addc_u32 s70, s70, 0
	s_mov_b64 s[54:55], s[0:1]
	s_cmp_gt_u32 s71, 41
	s_cbranch_scc0 .LBB0_930
	s_barrier
	s_and_b64 vcc, exec, s[48:49]
	s_cbranch_vccz .LBB0_933
	s_barrier
